# ILV=2 plus s_sleep 1 pacing between DMA groups in L slot
# baseline (speedup 1.0000x reference)
; #define PG8_STAGE(bufoff, gbase, voff) do { _Pragma("unroll") for (int _i = 0; _i < 2; ++_i) \
;         __builtin_amdgcn_global_load_lds((const unsigned*)((const char*)(gbase) + (voff)[_i]), (PG8_LAS unsigned*)(lds + (bufoff) + ldsw + _i * 8192), 16, 0, 0); } while (0)
; #define PG8_LDA(dst, b, h) do { _Pragma("unroll") for (int m = 0; m < 4; ++m) _Pragma("unroll") for (int k = 0; k < 2; ++k) dst[m][k] = *(const PG8_LAS bf16x8*)(lds + PG8_SA(b, h) + aoff + m * 2048 + k * 1024); } while (0)
; #define PG8_LDB(dst, b, h) do { _Pragma("unroll") for (int n = 0; n < 2; ++n) _Pragma("unroll") for (int k = 0; k < 2; ++k) dst[n][k] = *(const PG8_LAS bf16x8*)(lds + PG8_SB(b, h) + boff + n * 2048 + k * 1024); } while (0)
; #define PG8_WAIT_V(n) asm volatile("s_waitcnt vmcnt(" #n ")" ::: "memory")
; #define PG8_WAIT_L(n) asm volatile("s_waitcnt lgkmcnt(" #n ")" ::: "memory")
; template <class Epi, class Sched, bool ALIGN_EPI>
; __device__ __forceinline__ void gemm_phase(PG8_LAS unsigned char* lds, const Gemm g, const Sched& S, const Epi& E) {
;     ...
;             const char* a1 = cA + (size_t)(t + 1) * kstepA;
;             const char* a2 = last ? nA : cA + (size_t)(t + 2) * kstepA; const char* b2 = last ? nB : cB + (size_t)(t + 2) * kstep;
;             const char* a3 = a2 + kstepA; const char* b3 = b2 + kstep;
;             PG8_LDB(B0, 0, 0); PG8_LDB(B1, 0, 1); PG8_SCHED; PG8_LDA(At, 0, 0); PG8_STAGE(PG8_SA(1, 1), a1 + hstepA, voffA);
;             PG8_WAIT_V(8); PG8_WAIT_L(0); PG8_BAR; PG8_MMA(0, 0, At, B0); PG8_MMA(0, 1, At, B1); PG8_BAR; PG8_SCHED;
;             PG8_LDA(At, 0, 1); PG8_STAGE(PG8_SB(0, 0), b2, voffB); PG8_STAGE(PG8_SB(0, 1), b2 + hstepB, voffB); PG8_STAGE(PG8_SA(0, 0), a2, voffA);
;             PG8_WAIT_V(8); PG8_WAIT_L(0); PG8_BAR; PG8_MMA(1, 0, At, B0); PG8_MMA(1, 1, At, B1); PG8_BAR; PG8_SCHED;
;             PG8_LDB(B0, 1, 0); PG8_LDB(B1, 1, 1); PG8_SCHED; PG8_LDA(At, 1, 0); PG8_STAGE(PG8_SA(0, 1), a2 + hstepA, voffA);
;             PG8_WAIT_V(8); PG8_WAIT_L(0); PG8_BAR; PG8_MMA(0, 0, At, B0); PG8_MMA(0, 1, At, B1); PG8_BAR; PG8_SCHED;
;             PG8_LDA(At, 1, 1); PG8_STAGE(PG8_SB(1, 0), b3, voffB); PG8_STAGE(PG8_SB(1, 1), b3 + hstepB, voffB); PG8_STAGE(PG8_SA(1, 0), a3, voffA);
;             PG8_WAIT_V(8); PG8_WAIT_L(0); PG8_BAR; PG8_MMA(1, 0, At, B0); PG8_MMA(1, 1, At, B1); PG8_BAR; PG8_SCHED;
;         }
.Lp8k_A_loop:
	ds_read_b128 v[190:193], v155 offset:0
	ds_read_b128 v[194:197], v155 offset:1024
	ds_read_b128 v[198:201], v155 offset:2048
	s_add_i32 m0, s2, 0x18000
	s_nop 0
	global_load_lds_dwordx4 v134, s[28:29]
	s_sleep 1
	ds_read_b128 v[202:205], v155 offset:3072
	ds_read_b128 v[206:209], v155 offset:4096
	ds_read_b128 v[210:213], v155 offset:5120
	s_add_i32 m0, s2, 0x1a000
	s_nop 0
	global_load_lds_dwordx4 v130, s[28:29]
	s_sleep 1
	ds_read_b128 v[214:217], v155 offset:6144
	ds_read_b128 v[218:221], v155 offset:7168
	ds_read_b128 v[156:159], v153 offset:0
	s_add_u32 s30, s28, 0x20000
	s_addc_u32 s31, s29, 0
	s_add_i32 m0, s2, 0x19000
	s_nop 0
	global_load_lds_dwordx4 v134, s[30:31]
	s_sleep 1
	ds_read_b128 v[160:163], v153 offset:1024
	ds_read_b128 v[164:167], v153 offset:2048
	ds_read_b128 v[168:171], v153 offset:3072
	s_add_i32 m0, s2, 0x1b000
	s_nop 0
	global_load_lds_dwordx4 v130, s[30:31]
	s_sleep 1
	ds_read_b128 v[174:177], v153 offset:16384
	ds_read_b128 v[178:181], v153 offset:17408
	ds_read_b128 v[182:185], v153 offset:18432
	s_add_u32 s30, s28, 0x80000
	s_addc_u32 s31, s29, 0
	s_add_i32 m0, s2, 0x1c000
	s_nop 0
	global_load_lds_dwordx4 v134, s[30:31]
	s_sleep 1
	ds_read_b128 v[186:189], v153 offset:19456
	ds_read_b128 v[222:225], v155 offset:16384
	ds_read_b128 v[226:229], v155 offset:17408
	s_add_i32 m0, s2, 0x1e000
	s_nop 0
	global_load_lds_dwordx4 v130, s[30:31]
	s_sleep 1
	ds_read_b128 v[230:233], v155 offset:18432
	ds_read_b128 v[234:237], v155 offset:19456
	ds_read_b128 v[238:241], v155 offset:20480
	s_add_u32 s30, s28, 0xa0000
	s_addc_u32 s31, s29, 0
	s_add_i32 m0, s2, 0x1d000
	s_nop 0
	global_load_lds_dwordx4 v134, s[30:31]
	s_sleep 1
	ds_read_b128 v[242:245], v155 offset:21504
	ds_read_b128 v[246:249], v155 offset:22528
	ds_read_b128 v[250:253], v155 offset:23552
	s_add_i32 m0, s2, 0x1f000
	s_nop 0
	global_load_lds_dwordx4 v130, s[30:31]
	s_add_u32 s28, s28, 0x80
	s_addc_u32 s29, s29, 0
	s_waitcnt vmcnt(8) lgkmcnt(0)
	s_barrier
	s_setprio 1
	v_mfma_f32_16x16x32_bf16 v[126:129], v[156:159], v[190:193], v[126:129]
	v_mfma_f32_16x16x32_bf16 v[126:129], v[160:163], v[194:197], v[126:129]
	v_mfma_f32_16x16x32_bf16 v[122:125], v[168:171], v[194:197], v[122:125]
	v_mfma_f32_16x16x32_bf16 v[122:125], v[164:167], v[190:193], v[122:125]
	v_mfma_f32_16x16x32_bf16 v[118:121], v[174:177], v[190:193], v[118:121]
	v_mfma_f32_16x16x32_bf16 v[118:121], v[178:181], v[194:197], v[118:121]
	v_mfma_f32_16x16x32_bf16 v[114:117], v[186:189], v[194:197], v[114:117]
	v_mfma_f32_16x16x32_bf16 v[114:117], v[182:185], v[190:193], v[114:117]
	v_mfma_f32_16x16x32_bf16 v[98:101], v[182:185], v[198:201], v[98:101]
	v_mfma_f32_16x16x32_bf16 v[98:101], v[186:189], v[202:205], v[98:101]
	v_mfma_f32_16x16x32_bf16 v[102:105], v[178:181], v[202:205], v[102:105]
	v_mfma_f32_16x16x32_bf16 v[102:105], v[174:177], v[198:201], v[102:105]
	v_mfma_f32_16x16x32_bf16 v[106:109], v[164:167], v[198:201], v[106:109]
	v_mfma_f32_16x16x32_bf16 v[106:109], v[168:171], v[202:205], v[106:109]
	v_mfma_f32_16x16x32_bf16 v[110:113], v[160:163], v[202:205], v[110:113]
	v_mfma_f32_16x16x32_bf16 v[110:113], v[156:159], v[198:201], v[110:113]
	v_mfma_f32_16x16x32_bf16 v[94:97], v[156:159], v[206:209], v[94:97]
	v_mfma_f32_16x16x32_bf16 v[94:97], v[160:163], v[210:213], v[94:97]
	v_mfma_f32_16x16x32_bf16 v[90:93], v[168:171], v[210:213], v[90:93]
	v_mfma_f32_16x16x32_bf16 v[90:93], v[164:167], v[206:209], v[90:93]
	v_mfma_f32_16x16x32_bf16 v[86:89], v[174:177], v[206:209], v[86:89]
	v_mfma_f32_16x16x32_bf16 v[86:89], v[178:181], v[210:213], v[86:89]
	v_mfma_f32_16x16x32_bf16 v[82:85], v[186:189], v[210:213], v[82:85]
	v_mfma_f32_16x16x32_bf16 v[82:85], v[182:185], v[206:209], v[82:85]
	v_mfma_f32_16x16x32_bf16 v[66:69], v[182:185], v[214:217], v[66:69]
	v_mfma_f32_16x16x32_bf16 v[66:69], v[186:189], v[218:221], v[66:69]
	v_mfma_f32_16x16x32_bf16 v[70:73], v[178:181], v[218:221], v[70:73]
	v_mfma_f32_16x16x32_bf16 v[70:73], v[174:177], v[214:217], v[70:73]
	v_mfma_f32_16x16x32_bf16 v[74:77], v[164:167], v[214:217], v[74:77]
	v_mfma_f32_16x16x32_bf16 v[74:77], v[168:171], v[218:221], v[74:77]
	v_mfma_f32_16x16x32_bf16 v[78:81], v[160:163], v[218:221], v[78:81]
	v_mfma_f32_16x16x32_bf16 v[78:81], v[156:159], v[214:217], v[78:81]
	v_mfma_f32_16x16x32_bf16 v[62:65], v[156:159], v[222:225], v[62:65]
	v_mfma_f32_16x16x32_bf16 v[62:65], v[160:163], v[226:229], v[62:65]
	v_mfma_f32_16x16x32_bf16 v[58:61], v[168:171], v[226:229], v[58:61]
	v_mfma_f32_16x16x32_bf16 v[58:61], v[164:167], v[222:225], v[58:61]
	v_mfma_f32_16x16x32_bf16 v[54:57], v[174:177], v[222:225], v[54:57]
	v_mfma_f32_16x16x32_bf16 v[54:57], v[178:181], v[226:229], v[54:57]
	v_mfma_f32_16x16x32_bf16 v[50:53], v[186:189], v[226:229], v[50:53]
	v_mfma_f32_16x16x32_bf16 v[50:53], v[182:185], v[222:225], v[50:53]
	v_mfma_f32_16x16x32_bf16 v[34:37], v[182:185], v[230:233], v[34:37]
	v_mfma_f32_16x16x32_bf16 v[34:37], v[186:189], v[234:237], v[34:37]
	v_mfma_f32_16x16x32_bf16 v[38:41], v[178:181], v[234:237], v[38:41]
	v_mfma_f32_16x16x32_bf16 v[38:41], v[174:177], v[230:233], v[38:41]
	v_mfma_f32_16x16x32_bf16 v[42:45], v[164:167], v[230:233], v[42:45]
	v_mfma_f32_16x16x32_bf16 v[42:45], v[168:171], v[234:237], v[42:45]
	v_mfma_f32_16x16x32_bf16 v[46:49], v[160:163], v[234:237], v[46:49]
	v_mfma_f32_16x16x32_bf16 v[46:49], v[156:159], v[230:233], v[46:49]
	v_mfma_f32_16x16x32_bf16 v[30:33], v[156:159], v[238:241], v[30:33]
	v_mfma_f32_16x16x32_bf16 v[30:33], v[160:163], v[242:245], v[30:33]
	v_mfma_f32_16x16x32_bf16 v[26:29], v[168:171], v[242:245], v[26:29]
	v_mfma_f32_16x16x32_bf16 v[26:29], v[164:167], v[238:241], v[26:29]
	v_mfma_f32_16x16x32_bf16 v[22:25], v[174:177], v[238:241], v[22:25]
	v_mfma_f32_16x16x32_bf16 v[22:25], v[178:181], v[242:245], v[22:25]
	v_mfma_f32_16x16x32_bf16 v[18:21], v[186:189], v[242:245], v[18:21]
	v_mfma_f32_16x16x32_bf16 v[18:21], v[182:185], v[238:241], v[18:21]
	v_mfma_f32_16x16x32_bf16 v[2:5], v[182:185], v[246:249], v[2:5]
	v_mfma_f32_16x16x32_bf16 v[2:5], v[186:189], v[250:253], v[2:5]
	v_mfma_f32_16x16x32_bf16 v[6:9], v[178:181], v[250:253], v[6:9]
	v_mfma_f32_16x16x32_bf16 v[6:9], v[174:177], v[246:249], v[6:9]
	v_mfma_f32_16x16x32_bf16 v[10:13], v[164:167], v[246:249], v[10:13]
	v_mfma_f32_16x16x32_bf16 v[10:13], v[168:171], v[250:253], v[10:13]
	v_mfma_f32_16x16x32_bf16 v[14:17], v[160:163], v[250:253], v[14:17]
	v_mfma_f32_16x16x32_bf16 v[14:17], v[156:159], v[246:249], v[14:17]
	s_setprio 0
	s_waitcnt vmcnt(0)
	s_barrier
; #define PG8_STAGE(bufoff, gbase, voff) do { _Pragma("unroll") for (int _i = 0; _i < 2; ++_i) \
;         __builtin_amdgcn_global_load_lds((const unsigned*)((const char*)(gbase) + (voff)[_i]), (PG8_LAS unsigned*)(lds + (bufoff) + ldsw + _i * 8192), 16, 0, 0); } while (0)
; #define PG8_LDA(dst, b, h) do { _Pragma("unroll") for (int m = 0; m < 4; ++m) _Pragma("unroll") for (int k = 0; k < 2; ++k) dst[m][k] = *(const PG8_LAS bf16x8*)(lds + PG8_SA(b, h) + aoff + m * 2048 + k * 1024); } while (0)
; #define PG8_LDB(dst, b, h) do { _Pragma("unroll") for (int n = 0; n < 2; ++n) _Pragma("unroll") for (int k = 0; k < 2; ++k) dst[n][k] = *(const PG8_LAS bf16x8*)(lds + PG8_SB(b, h) + boff + n * 2048 + k * 1024); } while (0)
; #define PG8_WAIT_V(n) asm volatile("s_waitcnt vmcnt(" #n ")" ::: "memory")
; #define PG8_WAIT_L(n) asm volatile("s_waitcnt lgkmcnt(" #n ")" ::: "memory")
; template <class Epi, class Sched, bool ALIGN_EPI>
; __device__ __forceinline__ void gemm_phase(PG8_LAS unsigned char* lds, const Gemm g, const Sched& S, const Epi& E) {
;     ...
;             const char* a1 = cA + (size_t)(t + 1) * kstepA;
;             const char* a2 = last ? nA : cA + (size_t)(t + 2) * kstepA; const char* b2 = last ? nB : cB + (size_t)(t + 2) * kstep;
;             const char* a3 = a2 + kstepA; const char* b3 = b2 + kstep;
;             PG8_LDB(B0, 0, 0); PG8_LDB(B1, 0, 1); PG8_SCHED; PG8_LDA(At, 0, 0); PG8_STAGE(PG8_SA(1, 1), a1 + hstepA, voffA);
;             PG8_WAIT_V(8); PG8_WAIT_L(0); PG8_BAR; PG8_MMA(0, 0, At, B0); PG8_MMA(0, 1, At, B1); PG8_BAR; PG8_SCHED;
;             PG8_LDA(At, 0, 1); PG8_STAGE(PG8_SB(0, 0), b2, voffB); PG8_STAGE(PG8_SB(0, 1), b2 + hstepB, voffB); PG8_STAGE(PG8_SA(0, 0), a2, voffA);
;             PG8_WAIT_V(8); PG8_WAIT_L(0); PG8_BAR; PG8_MMA(1, 0, At, B0); PG8_MMA(1, 1, At, B1); PG8_BAR; PG8_SCHED;
;             PG8_LDB(B0, 1, 0); PG8_LDB(B1, 1, 1); PG8_SCHED; PG8_LDA(At, 1, 0); PG8_STAGE(PG8_SA(0, 1), a2 + hstepA, voffA);
;             PG8_WAIT_V(8); PG8_WAIT_L(0); PG8_BAR; PG8_MMA(0, 0, At, B0); PG8_MMA(0, 1, At, B1); PG8_BAR; PG8_SCHED;
;             PG8_LDA(At, 1, 1); PG8_STAGE(PG8_SB(1, 0), b3, voffB); PG8_STAGE(PG8_SB(1, 1), b3 + hstepB, voffB); PG8_STAGE(PG8_SA(1, 0), a3, voffA);
;             PG8_WAIT_V(8); PG8_WAIT_L(0); PG8_BAR; PG8_MMA(1, 0, At, B0); PG8_MMA(1, 1, At, B1); PG8_BAR; PG8_SCHED;
;         }
	ds_read_b128 v[190:193], v155 offset:32768
	ds_read_b128 v[194:197], v155 offset:33792
	ds_read_b128 v[198:201], v155 offset:34816
	s_cmp_eq_u32 s49, 15
	s_cselect_b32 s28, s50, s28
	s_cselect_b32 s29, s51, s29
	s_add_i32 m0, s2, 0x10000
	s_nop 0
	global_load_lds_dwordx4 v134, s[28:29]
	s_sleep 1
	ds_read_b128 v[202:205], v155 offset:35840
	ds_read_b128 v[206:209], v155 offset:36864
	ds_read_b128 v[210:213], v155 offset:37888
	s_add_i32 m0, s2, 0x12000
	s_nop 0
	global_load_lds_dwordx4 v130, s[28:29]
	s_sleep 1
	ds_read_b128 v[214:217], v155 offset:38912
	ds_read_b128 v[218:221], v155 offset:39936
	ds_read_b128 v[156:159], v153 offset:32768
	s_add_u32 s30, s28, 0x20000
	s_addc_u32 s31, s29, 0
	s_add_i32 m0, s2, 0x11000
	s_nop 0
	global_load_lds_dwordx4 v134, s[30:31]
	s_sleep 1
	ds_read_b128 v[160:163], v153 offset:33792
	ds_read_b128 v[164:167], v153 offset:34816
	ds_read_b128 v[168:171], v153 offset:35840
	s_add_i32 m0, s2, 0x13000
	s_nop 0
	global_load_lds_dwordx4 v130, s[30:31]
	s_sleep 1
	ds_read_b128 v[174:177], v153 offset:49152
	ds_read_b128 v[178:181], v153 offset:50176
	ds_read_b128 v[182:185], v153 offset:51200
	s_add_u32 s30, s28, 0x80000
	s_addc_u32 s31, s29, 0
	s_add_i32 m0, s2, 0x14000
	s_nop 0
	global_load_lds_dwordx4 v134, s[30:31]
	s_sleep 1
	ds_read_b128 v[186:189], v153 offset:52224
	ds_read_b128 v[222:225], v155 offset:49152
	ds_read_b128 v[226:229], v155 offset:50176
	s_add_i32 m0, s2, 0x16000
	s_nop 0
	global_load_lds_dwordx4 v130, s[30:31]
	s_sleep 1
	ds_read_b128 v[230:233], v155 offset:51200
	ds_read_b128 v[234:237], v155 offset:52224
	ds_read_b128 v[238:241], v155 offset:53248
	s_add_u32 s30, s28, 0xa0000
	s_addc_u32 s31, s29, 0
	s_add_i32 m0, s2, 0x15000
	s_nop 0
	global_load_lds_dwordx4 v134, s[30:31]
	s_sleep 1
	ds_read_b128 v[242:245], v155 offset:54272
	ds_read_b128 v[246:249], v155 offset:55296
	ds_read_b128 v[250:253], v155 offset:56320
	s_add_i32 m0, s2, 0x17000
	s_nop 0
	global_load_lds_dwordx4 v130, s[30:31]
	s_add_u32 s28, s28, 0x80
	s_addc_u32 s29, s29, 0
	s_waitcnt vmcnt(8) lgkmcnt(0)
	s_barrier
	s_setprio 1
	v_mfma_f32_16x16x32_bf16 v[126:129], v[156:159], v[190:193], v[126:129]
	v_mfma_f32_16x16x32_bf16 v[126:129], v[160:163], v[194:197], v[126:129]
	v_mfma_f32_16x16x32_bf16 v[122:125], v[168:171], v[194:197], v[122:125]
	v_mfma_f32_16x16x32_bf16 v[122:125], v[164:167], v[190:193], v[122:125]
	v_mfma_f32_16x16x32_bf16 v[118:121], v[174:177], v[190:193], v[118:121]
	v_mfma_f32_16x16x32_bf16 v[118:121], v[178:181], v[194:197], v[118:121]
	v_mfma_f32_16x16x32_bf16 v[114:117], v[186:189], v[194:197], v[114:117]
	v_mfma_f32_16x16x32_bf16 v[114:117], v[182:185], v[190:193], v[114:117]
	v_mfma_f32_16x16x32_bf16 v[98:101], v[182:185], v[198:201], v[98:101]
	v_mfma_f32_16x16x32_bf16 v[98:101], v[186:189], v[202:205], v[98:101]
	v_mfma_f32_16x16x32_bf16 v[102:105], v[178:181], v[202:205], v[102:105]
	v_mfma_f32_16x16x32_bf16 v[102:105], v[174:177], v[198:201], v[102:105]
	v_mfma_f32_16x16x32_bf16 v[106:109], v[164:167], v[198:201], v[106:109]
	v_mfma_f32_16x16x32_bf16 v[106:109], v[168:171], v[202:205], v[106:109]
	v_mfma_f32_16x16x32_bf16 v[110:113], v[160:163], v[202:205], v[110:113]
	v_mfma_f32_16x16x32_bf16 v[110:113], v[156:159], v[198:201], v[110:113]
	v_mfma_f32_16x16x32_bf16 v[94:97], v[156:159], v[206:209], v[94:97]
	v_mfma_f32_16x16x32_bf16 v[94:97], v[160:163], v[210:213], v[94:97]
	v_mfma_f32_16x16x32_bf16 v[90:93], v[168:171], v[210:213], v[90:93]
	v_mfma_f32_16x16x32_bf16 v[90:93], v[164:167], v[206:209], v[90:93]
	v_mfma_f32_16x16x32_bf16 v[86:89], v[174:177], v[206:209], v[86:89]
	v_mfma_f32_16x16x32_bf16 v[86:89], v[178:181], v[210:213], v[86:89]
	v_mfma_f32_16x16x32_bf16 v[82:85], v[186:189], v[210:213], v[82:85]
	v_mfma_f32_16x16x32_bf16 v[82:85], v[182:185], v[206:209], v[82:85]
	v_mfma_f32_16x16x32_bf16 v[66:69], v[182:185], v[214:217], v[66:69]
	v_mfma_f32_16x16x32_bf16 v[66:69], v[186:189], v[218:221], v[66:69]
	v_mfma_f32_16x16x32_bf16 v[70:73], v[178:181], v[218:221], v[70:73]
	v_mfma_f32_16x16x32_bf16 v[70:73], v[174:177], v[214:217], v[70:73]
	v_mfma_f32_16x16x32_bf16 v[74:77], v[164:167], v[214:217], v[74:77]
	v_mfma_f32_16x16x32_bf16 v[74:77], v[168:171], v[218:221], v[74:77]
	v_mfma_f32_16x16x32_bf16 v[78:81], v[160:163], v[218:221], v[78:81]
	v_mfma_f32_16x16x32_bf16 v[78:81], v[156:159], v[214:217], v[78:81]
	v_mfma_f32_16x16x32_bf16 v[62:65], v[156:159], v[222:225], v[62:65]
	v_mfma_f32_16x16x32_bf16 v[62:65], v[160:163], v[226:229], v[62:65]
	v_mfma_f32_16x16x32_bf16 v[58:61], v[168:171], v[226:229], v[58:61]
	v_mfma_f32_16x16x32_bf16 v[58:61], v[164:167], v[222:225], v[58:61]
	v_mfma_f32_16x16x32_bf16 v[54:57], v[174:177], v[222:225], v[54:57]
	v_mfma_f32_16x16x32_bf16 v[54:57], v[178:181], v[226:229], v[54:57]
	v_mfma_f32_16x16x32_bf16 v[50:53], v[186:189], v[226:229], v[50:53]
	v_mfma_f32_16x16x32_bf16 v[50:53], v[182:185], v[222:225], v[50:53]
	v_mfma_f32_16x16x32_bf16 v[34:37], v[182:185], v[230:233], v[34:37]
	v_mfma_f32_16x16x32_bf16 v[34:37], v[186:189], v[234:237], v[34:37]
	v_mfma_f32_16x16x32_bf16 v[38:41], v[178:181], v[234:237], v[38:41]
	v_mfma_f32_16x16x32_bf16 v[38:41], v[174:177], v[230:233], v[38:41]
	v_mfma_f32_16x16x32_bf16 v[42:45], v[164:167], v[230:233], v[42:45]
	v_mfma_f32_16x16x32_bf16 v[42:45], v[168:171], v[234:237], v[42:45]
	v_mfma_f32_16x16x32_bf16 v[46:49], v[160:163], v[234:237], v[46:49]
	v_mfma_f32_16x16x32_bf16 v[46:49], v[156:159], v[230:233], v[46:49]
	v_mfma_f32_16x16x32_bf16 v[30:33], v[156:159], v[238:241], v[30:33]
	v_mfma_f32_16x16x32_bf16 v[30:33], v[160:163], v[242:245], v[30:33]
	v_mfma_f32_16x16x32_bf16 v[26:29], v[168:171], v[242:245], v[26:29]
	v_mfma_f32_16x16x32_bf16 v[26:29], v[164:167], v[238:241], v[26:29]
	v_mfma_f32_16x16x32_bf16 v[22:25], v[174:177], v[238:241], v[22:25]
	v_mfma_f32_16x16x32_bf16 v[22:25], v[178:181], v[242:245], v[22:25]
	v_mfma_f32_16x16x32_bf16 v[18:21], v[186:189], v[242:245], v[18:21]
	v_mfma_f32_16x16x32_bf16 v[18:21], v[182:185], v[238:241], v[18:21]
	v_mfma_f32_16x16x32_bf16 v[2:5], v[182:185], v[246:249], v[2:5]
	v_mfma_f32_16x16x32_bf16 v[2:5], v[186:189], v[250:253], v[2:5]
	v_mfma_f32_16x16x32_bf16 v[6:9], v[178:181], v[250:253], v[6:9]
	v_mfma_f32_16x16x32_bf16 v[6:9], v[174:177], v[246:249], v[6:9]
	v_mfma_f32_16x16x32_bf16 v[10:13], v[164:167], v[246:249], v[10:13]
	v_mfma_f32_16x16x32_bf16 v[10:13], v[168:171], v[250:253], v[10:13]
	v_mfma_f32_16x16x32_bf16 v[14:17], v[160:163], v[250:253], v[14:17]
	v_mfma_f32_16x16x32_bf16 v[14:17], v[156:159], v[246:249], v[14:17]
	s_setprio 0
	s_waitcnt vmcnt(0)
	s_barrier
	s_add_i32 s49, s49, 1
	s_cmp_lt_u32 s49, 16
	s_cbranch_scc1 .Lp8k_A_loop
	s_branch .Lp8k_done

; #define PG8_STAGE(bufoff, gbase, voff) do { _Pragma("unroll") for (int _i = 0; _i < 2; ++_i) \
;         __builtin_amdgcn_global_load_lds((const unsigned*)((const char*)(gbase) + (voff)[_i]), (PG8_LAS unsigned*)(lds + (bufoff) + ldsw + _i * 8192), 16, 0, 0); } while (0)
; #define PG8_LDA(dst, b, h) do { _Pragma("unroll") for (int m = 0; m < 4; ++m) _Pragma("unroll") for (int k = 0; k < 2; ++k) dst[m][k] = *(const PG8_LAS bf16x8*)(lds + PG8_SA(b, h) + aoff + m * 2048 + k * 1024); } while (0)
; #define PG8_LDB(dst, b, h) do { _Pragma("unroll") for (int n = 0; n < 2; ++n) _Pragma("unroll") for (int k = 0; k < 2; ++k) dst[n][k] = *(const PG8_LAS bf16x8*)(lds + PG8_SB(b, h) + boff + n * 2048 + k * 1024); } while (0)
; #define PG8_WAIT_V(n) asm volatile("s_waitcnt vmcnt(" #n ")" ::: "memory")
; #define PG8_WAIT_L(n) asm volatile("s_waitcnt lgkmcnt(" #n ")" ::: "memory")
; template <class Epi, class Sched, bool ALIGN_EPI>
; __device__ __forceinline__ void gemm_phase(PG8_LAS unsigned char* lds, const Gemm g, const Sched& S, const Epi& E) {
;     ...
;             const char* a1 = cA + (size_t)(t + 1) * kstepA;
;             const char* a2 = last ? nA : cA + (size_t)(t + 2) * kstepA; const char* b2 = last ? nB : cB + (size_t)(t + 2) * kstep;
;             const char* a3 = a2 + kstepA; const char* b3 = b2 + kstep;
;             PG8_LDB(B0, 0, 0); PG8_LDB(B1, 0, 1); PG8_SCHED; PG8_LDA(At, 0, 0); PG8_STAGE(PG8_SA(1, 1), a1 + hstepA, voffA);
;             PG8_WAIT_V(8); PG8_WAIT_L(0); PG8_BAR; PG8_MMA(0, 0, At, B0); PG8_MMA(0, 1, At, B1); PG8_BAR; PG8_SCHED;
;             PG8_LDA(At, 0, 1); PG8_STAGE(PG8_SB(0, 0), b2, voffB); PG8_STAGE(PG8_SB(0, 1), b2 + hstepB, voffB); PG8_STAGE(PG8_SA(0, 0), a2, voffA);
;             PG8_WAIT_V(8); PG8_WAIT_L(0); PG8_BAR; PG8_MMA(1, 0, At, B0); PG8_MMA(1, 1, At, B1); PG8_BAR; PG8_SCHED;
;             PG8_LDB(B0, 1, 0); PG8_LDB(B1, 1, 1); PG8_SCHED; PG8_LDA(At, 1, 0); PG8_STAGE(PG8_SA(0, 1), a2 + hstepA, voffA);
;             PG8_WAIT_V(8); PG8_WAIT_L(0); PG8_BAR; PG8_MMA(0, 0, At, B0); PG8_MMA(0, 1, At, B1); PG8_BAR; PG8_SCHED;
;             PG8_LDA(At, 1, 1); PG8_STAGE(PG8_SB(1, 0), b3, voffB); PG8_STAGE(PG8_SB(1, 1), b3 + hstepB, voffB); PG8_STAGE(PG8_SA(1, 0), a3, voffA);
;             PG8_WAIT_V(8); PG8_WAIT_L(0); PG8_BAR; PG8_MMA(1, 0, At, B0); PG8_MMA(1, 1, At, B1); PG8_BAR; PG8_SCHED;
;         }
.Lp8k_B_loop:
	ds_read_b128 v[190:193], v155 offset:0
	ds_read_b128 v[194:197], v155 offset:1024
	ds_read_b128 v[198:201], v155 offset:2048
	s_add_i32 m0, s2, 0xa000
	s_nop 0
	global_load_lds_dwordx4 v132, s[28:29]
	s_sleep 1
	ds_read_b128 v[202:205], v155 offset:3072
	ds_read_b128 v[206:209], v155 offset:4096
	ds_read_b128 v[210:213], v155 offset:5120
	s_add_u32 s30, s28, 0x20000
	s_addc_u32 s31, s29, 0
	s_add_i32 m0, s2, 0xb000
	s_nop 0
	global_load_lds_dwordx4 v132, s[30:31]
	s_sleep 1
	ds_read_b128 v[214:217], v155 offset:6144
	ds_read_b128 v[218:221], v155 offset:7168
	ds_read_b128 v[156:159], v153 offset:0
	s_add_u32 s30, s28, 0x80000
	s_addc_u32 s31, s29, 0
	s_add_i32 m0, s2, 0xe000
	s_nop 0
	global_load_lds_dwordx4 v132, s[30:31]
	s_sleep 1
	ds_read_b128 v[160:163], v153 offset:1024
	ds_read_b128 v[164:167], v153 offset:2048
	ds_read_b128 v[168:171], v153 offset:3072
	s_add_u32 s30, s28, 0xa0000
	s_addc_u32 s31, s29, 0
	s_add_i32 m0, s2, 0xf000
	s_nop 0
	global_load_lds_dwordx4 v132, s[30:31]
	s_sleep 1
	ds_read_b128 v[174:177], v153 offset:16384
	ds_read_b128 v[178:181], v153 offset:17408
	ds_read_b128 v[182:185], v153 offset:18432
	s_add_u32 s34, s28, 0x80
	s_addc_u32 s35, s29, 0
	s_cmp_eq_u32 s49, 15
	s_cselect_b32 s34, s50, s34
	s_cselect_b32 s35, s51, s35
	s_add_i32 m0, s2, 0x0
	s_nop 0
	global_load_lds_dwordx4 v136, s[34:35]
	s_sleep 1
	ds_read_b128 v[186:189], v153 offset:19456
	ds_read_b128 v[222:225], v155 offset:16384
	ds_read_b128 v[226:229], v155 offset:17408
	s_add_u32 s30, s34, 0x20000
	s_addc_u32 s31, s35, 0
	s_add_i32 m0, s2, 0x1000
	s_nop 0
	global_load_lds_dwordx4 v136, s[30:31]
	s_sleep 1
	ds_read_b128 v[230:233], v155 offset:18432
	ds_read_b128 v[234:237], v155 offset:19456
	ds_read_b128 v[238:241], v155 offset:20480
	s_add_u32 s30, s34, 0x80000
	s_addc_u32 s31, s35, 0
	s_add_i32 m0, s2, 0x4000
	s_nop 0
	global_load_lds_dwordx4 v136, s[30:31]
	s_sleep 1
	ds_read_b128 v[242:245], v155 offset:21504
	ds_read_b128 v[246:249], v155 offset:22528
	ds_read_b128 v[250:253], v155 offset:23552
	s_add_u32 s30, s34, 0xa0000
	s_addc_u32 s31, s35, 0
	s_add_i32 m0, s2, 0x5000
	s_nop 0
	global_load_lds_dwordx4 v136, s[30:31]
	s_add_u32 s28, s28, 0x80
	s_addc_u32 s29, s29, 0
	s_waitcnt vmcnt(8) lgkmcnt(0)
	s_barrier
	s_setprio 1
	v_mfma_f32_16x16x32_bf16 v[126:129], v[156:159], v[190:193], v[126:129]
	v_mfma_f32_16x16x32_bf16 v[126:129], v[160:163], v[194:197], v[126:129]
	v_mfma_f32_16x16x32_bf16 v[122:125], v[168:171], v[194:197], v[122:125]
	v_mfma_f32_16x16x32_bf16 v[122:125], v[164:167], v[190:193], v[122:125]
	v_mfma_f32_16x16x32_bf16 v[118:121], v[174:177], v[190:193], v[118:121]
	v_mfma_f32_16x16x32_bf16 v[118:121], v[178:181], v[194:197], v[118:121]
	v_mfma_f32_16x16x32_bf16 v[114:117], v[186:189], v[194:197], v[114:117]
	v_mfma_f32_16x16x32_bf16 v[114:117], v[182:185], v[190:193], v[114:117]
	v_mfma_f32_16x16x32_bf16 v[98:101], v[182:185], v[198:201], v[98:101]
	v_mfma_f32_16x16x32_bf16 v[98:101], v[186:189], v[202:205], v[98:101]
	v_mfma_f32_16x16x32_bf16 v[102:105], v[178:181], v[202:205], v[102:105]
	v_mfma_f32_16x16x32_bf16 v[102:105], v[174:177], v[198:201], v[102:105]
	v_mfma_f32_16x16x32_bf16 v[106:109], v[164:167], v[198:201], v[106:109]
	v_mfma_f32_16x16x32_bf16 v[106:109], v[168:171], v[202:205], v[106:109]
	v_mfma_f32_16x16x32_bf16 v[110:113], v[160:163], v[202:205], v[110:113]
	v_mfma_f32_16x16x32_bf16 v[110:113], v[156:159], v[198:201], v[110:113]
	v_mfma_f32_16x16x32_bf16 v[94:97], v[156:159], v[206:209], v[94:97]
	v_mfma_f32_16x16x32_bf16 v[94:97], v[160:163], v[210:213], v[94:97]
	v_mfma_f32_16x16x32_bf16 v[90:93], v[168:171], v[210:213], v[90:93]
	v_mfma_f32_16x16x32_bf16 v[90:93], v[164:167], v[206:209], v[90:93]
	v_mfma_f32_16x16x32_bf16 v[86:89], v[174:177], v[206:209], v[86:89]
	v_mfma_f32_16x16x32_bf16 v[86:89], v[178:181], v[210:213], v[86:89]
	v_mfma_f32_16x16x32_bf16 v[82:85], v[186:189], v[210:213], v[82:85]
	v_mfma_f32_16x16x32_bf16 v[82:85], v[182:185], v[206:209], v[82:85]
	v_mfma_f32_16x16x32_bf16 v[66:69], v[182:185], v[214:217], v[66:69]
	v_mfma_f32_16x16x32_bf16 v[66:69], v[186:189], v[218:221], v[66:69]
	v_mfma_f32_16x16x32_bf16 v[70:73], v[178:181], v[218:221], v[70:73]
	v_mfma_f32_16x16x32_bf16 v[70:73], v[174:177], v[214:217], v[70:73]
	v_mfma_f32_16x16x32_bf16 v[74:77], v[164:167], v[214:217], v[74:77]
	v_mfma_f32_16x16x32_bf16 v[74:77], v[168:171], v[218:221], v[74:77]
	v_mfma_f32_16x16x32_bf16 v[78:81], v[160:163], v[218:221], v[78:81]
	v_mfma_f32_16x16x32_bf16 v[78:81], v[156:159], v[214:217], v[78:81]
	v_mfma_f32_16x16x32_bf16 v[62:65], v[156:159], v[222:225], v[62:65]
	v_mfma_f32_16x16x32_bf16 v[62:65], v[160:163], v[226:229], v[62:65]
	v_mfma_f32_16x16x32_bf16 v[58:61], v[168:171], v[226:229], v[58:61]
	v_mfma_f32_16x16x32_bf16 v[58:61], v[164:167], v[222:225], v[58:61]
	v_mfma_f32_16x16x32_bf16 v[54:57], v[174:177], v[222:225], v[54:57]
	v_mfma_f32_16x16x32_bf16 v[54:57], v[178:181], v[226:229], v[54:57]
	v_mfma_f32_16x16x32_bf16 v[50:53], v[186:189], v[226:229], v[50:53]
	v_mfma_f32_16x16x32_bf16 v[50:53], v[182:185], v[222:225], v[50:53]
	v_mfma_f32_16x16x32_bf16 v[34:37], v[182:185], v[230:233], v[34:37]
	v_mfma_f32_16x16x32_bf16 v[34:37], v[186:189], v[234:237], v[34:37]
	v_mfma_f32_16x16x32_bf16 v[38:41], v[178:181], v[234:237], v[38:41]
	v_mfma_f32_16x16x32_bf16 v[38:41], v[174:177], v[230:233], v[38:41]
	v_mfma_f32_16x16x32_bf16 v[42:45], v[164:167], v[230:233], v[42:45]
	v_mfma_f32_16x16x32_bf16 v[42:45], v[168:171], v[234:237], v[42:45]
	v_mfma_f32_16x16x32_bf16 v[46:49], v[160:163], v[234:237], v[46:49]
	v_mfma_f32_16x16x32_bf16 v[46:49], v[156:159], v[230:233], v[46:49]
	v_mfma_f32_16x16x32_bf16 v[30:33], v[156:159], v[238:241], v[30:33]
	v_mfma_f32_16x16x32_bf16 v[30:33], v[160:163], v[242:245], v[30:33]
	v_mfma_f32_16x16x32_bf16 v[26:29], v[168:171], v[242:245], v[26:29]
	v_mfma_f32_16x16x32_bf16 v[26:29], v[164:167], v[238:241], v[26:29]
	v_mfma_f32_16x16x32_bf16 v[22:25], v[174:177], v[238:241], v[22:25]
	v_mfma_f32_16x16x32_bf16 v[22:25], v[178:181], v[242:245], v[22:25]
	v_mfma_f32_16x16x32_bf16 v[18:21], v[186:189], v[242:245], v[18:21]
	v_mfma_f32_16x16x32_bf16 v[18:21], v[182:185], v[238:241], v[18:21]
	v_mfma_f32_16x16x32_bf16 v[2:5], v[182:185], v[246:249], v[2:5]
	v_mfma_f32_16x16x32_bf16 v[2:5], v[186:189], v[250:253], v[2:5]
	v_mfma_f32_16x16x32_bf16 v[6:9], v[178:181], v[250:253], v[6:9]
	v_mfma_f32_16x16x32_bf16 v[6:9], v[174:177], v[246:249], v[6:9]
	v_mfma_f32_16x16x32_bf16 v[10:13], v[164:167], v[246:249], v[10:13]
	v_mfma_f32_16x16x32_bf16 v[10:13], v[168:171], v[250:253], v[10:13]
	v_mfma_f32_16x16x32_bf16 v[14:17], v[160:163], v[250:253], v[14:17]
	v_mfma_f32_16x16x32_bf16 v[14:17], v[156:159], v[246:249], v[14:17]
	s_setprio 0
	s_waitcnt vmcnt(0)
	s_barrier
; #define PG8_STAGE(bufoff, gbase, voff) do { _Pragma("unroll") for (int _i = 0; _i < 2; ++_i) \
;         __builtin_amdgcn_global_load_lds((const unsigned*)((const char*)(gbase) + (voff)[_i]), (PG8_LAS unsigned*)(lds + (bufoff) + ldsw + _i * 8192), 16, 0, 0); } while (0)
; #define PG8_LDA(dst, b, h) do { _Pragma("unroll") for (int m = 0; m < 4; ++m) _Pragma("unroll") for (int k = 0; k < 2; ++k) dst[m][k] = *(const PG8_LAS bf16x8*)(lds + PG8_SA(b, h) + aoff + m * 2048 + k * 1024); } while (0)
; #define PG8_LDB(dst, b, h) do { _Pragma("unroll") for (int n = 0; n < 2; ++n) _Pragma("unroll") for (int k = 0; k < 2; ++k) dst[n][k] = *(const PG8_LAS bf16x8*)(lds + PG8_SB(b, h) + boff + n * 2048 + k * 1024); } while (0)
; #define PG8_WAIT_V(n) asm volatile("s_waitcnt vmcnt(" #n ")" ::: "memory")
; #define PG8_WAIT_L(n) asm volatile("s_waitcnt lgkmcnt(" #n ")" ::: "memory")
; template <class Epi, class Sched, bool ALIGN_EPI>
; __device__ __forceinline__ void gemm_phase(PG8_LAS unsigned char* lds, const Gemm g, const Sched& S, const Epi& E) {
;     ...
;             const char* a1 = cA + (size_t)(t + 1) * kstepA;
;             const char* a2 = last ? nA : cA + (size_t)(t + 2) * kstepA; const char* b2 = last ? nB : cB + (size_t)(t + 2) * kstep;
;             const char* a3 = a2 + kstepA; const char* b3 = b2 + kstep;
;             PG8_LDB(B0, 0, 0); PG8_LDB(B1, 0, 1); PG8_SCHED; PG8_LDA(At, 0, 0); PG8_STAGE(PG8_SA(1, 1), a1 + hstepA, voffA);
;             PG8_WAIT_V(8); PG8_WAIT_L(0); PG8_BAR; PG8_MMA(0, 0, At, B0); PG8_MMA(0, 1, At, B1); PG8_BAR; PG8_SCHED;
;             PG8_LDA(At, 0, 1); PG8_STAGE(PG8_SB(0, 0), b2, voffB); PG8_STAGE(PG8_SB(0, 1), b2 + hstepB, voffB); PG8_STAGE(PG8_SA(0, 0), a2, voffA);
;             PG8_WAIT_V(8); PG8_WAIT_L(0); PG8_BAR; PG8_MMA(1, 0, At, B0); PG8_MMA(1, 1, At, B1); PG8_BAR; PG8_SCHED;
;             PG8_LDB(B0, 1, 0); PG8_LDB(B1, 1, 1); PG8_SCHED; PG8_LDA(At, 1, 0); PG8_STAGE(PG8_SA(0, 1), a2 + hstepA, voffA);
;             PG8_WAIT_V(8); PG8_WAIT_L(0); PG8_BAR; PG8_MMA(0, 0, At, B0); PG8_MMA(0, 1, At, B1); PG8_BAR; PG8_SCHED;
;             PG8_LDA(At, 1, 1); PG8_STAGE(PG8_SB(1, 0), b3, voffB); PG8_STAGE(PG8_SB(1, 1), b3 + hstepB, voffB); PG8_STAGE(PG8_SA(1, 0), a3, voffA);
;             PG8_WAIT_V(8); PG8_WAIT_L(0); PG8_BAR; PG8_MMA(1, 0, At, B0); PG8_MMA(1, 1, At, B1); PG8_BAR; PG8_SCHED;
;         }
	ds_read_b128 v[190:193], v155 offset:32768
	ds_read_b128 v[194:197], v155 offset:33792
	ds_read_b128 v[198:201], v155 offset:34816
	s_cmp_eq_u32 s49, 15
	s_cselect_b32 s28, s50, s28
	s_cselect_b32 s29, s51, s29
	s_add_i32 m0, s2, 0x2000
	s_nop 0
	global_load_lds_dwordx4 v132, s[28:29]
	s_sleep 1
	ds_read_b128 v[202:205], v155 offset:35840
	ds_read_b128 v[206:209], v155 offset:36864
	ds_read_b128 v[210:213], v155 offset:37888
	s_add_u32 s30, s28, 0x20000
	s_addc_u32 s31, s29, 0
	s_add_i32 m0, s2, 0x3000
	s_nop 0
	global_load_lds_dwordx4 v132, s[30:31]
	s_sleep 1
	ds_read_b128 v[214:217], v155 offset:38912
	ds_read_b128 v[218:221], v155 offset:39936
	ds_read_b128 v[156:159], v153 offset:32768
	s_add_u32 s30, s28, 0x80000
	s_addc_u32 s31, s29, 0
	s_add_i32 m0, s2, 0x6000
	s_nop 0
	global_load_lds_dwordx4 v132, s[30:31]
	s_sleep 1
	ds_read_b128 v[160:163], v153 offset:33792
	ds_read_b128 v[164:167], v153 offset:34816
	ds_read_b128 v[168:171], v153 offset:35840
	s_add_u32 s30, s28, 0xa0000
	s_addc_u32 s31, s29, 0
	s_add_i32 m0, s2, 0x7000
	s_nop 0
	global_load_lds_dwordx4 v132, s[30:31]
	s_sleep 1
	ds_read_b128 v[174:177], v153 offset:49152
	ds_read_b128 v[178:181], v153 offset:50176
	ds_read_b128 v[182:185], v153 offset:51200
	s_add_u32 s34, s28, 0x80
	s_addc_u32 s35, s29, 0
	s_add_i32 m0, s2, 0x8000
	s_nop 0
	global_load_lds_dwordx4 v136, s[34:35]
	s_sleep 1
	ds_read_b128 v[186:189], v153 offset:52224
	ds_read_b128 v[222:225], v155 offset:49152
	ds_read_b128 v[226:229], v155 offset:50176
	s_add_u32 s30, s34, 0x20000
	s_addc_u32 s31, s35, 0
	s_add_i32 m0, s2, 0x9000
	s_nop 0
	global_load_lds_dwordx4 v136, s[30:31]
	s_sleep 1
	ds_read_b128 v[230:233], v155 offset:51200
	ds_read_b128 v[234:237], v155 offset:52224
	ds_read_b128 v[238:241], v155 offset:53248
	s_add_u32 s30, s34, 0x80000
	s_addc_u32 s31, s35, 0
	s_add_i32 m0, s2, 0xc000
	s_nop 0
	global_load_lds_dwordx4 v136, s[30:31]
	s_sleep 1
	ds_read_b128 v[242:245], v155 offset:54272
	ds_read_b128 v[246:249], v155 offset:55296
	ds_read_b128 v[250:253], v155 offset:56320
	s_add_u32 s30, s34, 0xa0000
	s_addc_u32 s31, s35, 0
	s_add_i32 m0, s2, 0xd000
	s_nop 0
	global_load_lds_dwordx4 v136, s[30:31]
	s_add_u32 s28, s28, 0x80
	s_addc_u32 s29, s29, 0
	s_waitcnt vmcnt(8) lgkmcnt(0)
	s_barrier
	s_setprio 1
	v_mfma_f32_16x16x32_bf16 v[126:129], v[156:159], v[190:193], v[126:129]
	v_mfma_f32_16x16x32_bf16 v[126:129], v[160:163], v[194:197], v[126:129]
	v_mfma_f32_16x16x32_bf16 v[122:125], v[168:171], v[194:197], v[122:125]
	v_mfma_f32_16x16x32_bf16 v[122:125], v[164:167], v[190:193], v[122:125]
	v_mfma_f32_16x16x32_bf16 v[118:121], v[174:177], v[190:193], v[118:121]
	v_mfma_f32_16x16x32_bf16 v[118:121], v[178:181], v[194:197], v[118:121]
	v_mfma_f32_16x16x32_bf16 v[114:117], v[186:189], v[194:197], v[114:117]
	v_mfma_f32_16x16x32_bf16 v[114:117], v[182:185], v[190:193], v[114:117]
	v_mfma_f32_16x16x32_bf16 v[98:101], v[182:185], v[198:201], v[98:101]
	v_mfma_f32_16x16x32_bf16 v[98:101], v[186:189], v[202:205], v[98:101]
	v_mfma_f32_16x16x32_bf16 v[102:105], v[178:181], v[202:205], v[102:105]
	v_mfma_f32_16x16x32_bf16 v[102:105], v[174:177], v[198:201], v[102:105]
	v_mfma_f32_16x16x32_bf16 v[106:109], v[164:167], v[198:201], v[106:109]
	v_mfma_f32_16x16x32_bf16 v[106:109], v[168:171], v[202:205], v[106:109]
	v_mfma_f32_16x16x32_bf16 v[110:113], v[160:163], v[202:205], v[110:113]
	v_mfma_f32_16x16x32_bf16 v[110:113], v[156:159], v[198:201], v[110:113]
	v_mfma_f32_16x16x32_bf16 v[94:97], v[156:159], v[206:209], v[94:97]
	v_mfma_f32_16x16x32_bf16 v[94:97], v[160:163], v[210:213], v[94:97]
	v_mfma_f32_16x16x32_bf16 v[90:93], v[168:171], v[210:213], v[90:93]
	v_mfma_f32_16x16x32_bf16 v[90:93], v[164:167], v[206:209], v[90:93]
	v_mfma_f32_16x16x32_bf16 v[86:89], v[174:177], v[206:209], v[86:89]
	v_mfma_f32_16x16x32_bf16 v[86:89], v[178:181], v[210:213], v[86:89]
	v_mfma_f32_16x16x32_bf16 v[82:85], v[186:189], v[210:213], v[82:85]
	v_mfma_f32_16x16x32_bf16 v[82:85], v[182:185], v[206:209], v[82:85]
	v_mfma_f32_16x16x32_bf16 v[66:69], v[182:185], v[214:217], v[66:69]
	v_mfma_f32_16x16x32_bf16 v[66:69], v[186:189], v[218:221], v[66:69]
	v_mfma_f32_16x16x32_bf16 v[70:73], v[178:181], v[218:221], v[70:73]
	v_mfma_f32_16x16x32_bf16 v[70:73], v[174:177], v[214:217], v[70:73]
	v_mfma_f32_16x16x32_bf16 v[74:77], v[164:167], v[214:217], v[74:77]
	v_mfma_f32_16x16x32_bf16 v[74:77], v[168:171], v[218:221], v[74:77]
	v_mfma_f32_16x16x32_bf16 v[78:81], v[160:163], v[218:221], v[78:81]
	v_mfma_f32_16x16x32_bf16 v[78:81], v[156:159], v[214:217], v[78:81]
	v_mfma_f32_16x16x32_bf16 v[62:65], v[156:159], v[222:225], v[62:65]
	v_mfma_f32_16x16x32_bf16 v[62:65], v[160:163], v[226:229], v[62:65]
	v_mfma_f32_16x16x32_bf16 v[58:61], v[168:171], v[226:229], v[58:61]
	v_mfma_f32_16x16x32_bf16 v[58:61], v[164:167], v[222:225], v[58:61]
	v_mfma_f32_16x16x32_bf16 v[54:57], v[174:177], v[222:225], v[54:57]
	v_mfma_f32_16x16x32_bf16 v[54:57], v[178:181], v[226:229], v[54:57]
	v_mfma_f32_16x16x32_bf16 v[50:53], v[186:189], v[226:229], v[50:53]
	v_mfma_f32_16x16x32_bf16 v[50:53], v[182:185], v[222:225], v[50:53]
	v_mfma_f32_16x16x32_bf16 v[34:37], v[182:185], v[230:233], v[34:37]
	v_mfma_f32_16x16x32_bf16 v[34:37], v[186:189], v[234:237], v[34:37]
	v_mfma_f32_16x16x32_bf16 v[38:41], v[178:181], v[234:237], v[38:41]
	v_mfma_f32_16x16x32_bf16 v[38:41], v[174:177], v[230:233], v[38:41]
	v_mfma_f32_16x16x32_bf16 v[42:45], v[164:167], v[230:233], v[42:45]
	v_mfma_f32_16x16x32_bf16 v[42:45], v[168:171], v[234:237], v[42:45]
	v_mfma_f32_16x16x32_bf16 v[46:49], v[160:163], v[234:237], v[46:49]
	v_mfma_f32_16x16x32_bf16 v[46:49], v[156:159], v[230:233], v[46:49]
	v_mfma_f32_16x16x32_bf16 v[30:33], v[156:159], v[238:241], v[30:33]
	v_mfma_f32_16x16x32_bf16 v[30:33], v[160:163], v[242:245], v[30:33]
	v_mfma_f32_16x16x32_bf16 v[26:29], v[168:171], v[242:245], v[26:29]
	v_mfma_f32_16x16x32_bf16 v[26:29], v[164:167], v[238:241], v[26:29]
	v_mfma_f32_16x16x32_bf16 v[22:25], v[174:177], v[238:241], v[22:25]
	v_mfma_f32_16x16x32_bf16 v[22:25], v[178:181], v[242:245], v[22:25]
	v_mfma_f32_16x16x32_bf16 v[18:21], v[186:189], v[242:245], v[18:21]
	v_mfma_f32_16x16x32_bf16 v[18:21], v[182:185], v[238:241], v[18:21]
	v_mfma_f32_16x16x32_bf16 v[2:5], v[182:185], v[246:249], v[2:5]
	v_mfma_f32_16x16x32_bf16 v[2:5], v[186:189], v[250:253], v[2:5]
	v_mfma_f32_16x16x32_bf16 v[6:9], v[178:181], v[250:253], v[6:9]
	v_mfma_f32_16x16x32_bf16 v[6:9], v[174:177], v[246:249], v[6:9]
	v_mfma_f32_16x16x32_bf16 v[10:13], v[164:167], v[246:249], v[10:13]
	v_mfma_f32_16x16x32_bf16 v[10:13], v[168:171], v[250:253], v[10:13]
	v_mfma_f32_16x16x32_bf16 v[14:17], v[160:163], v[250:253], v[14:17]
	v_mfma_f32_16x16x32_bf16 v[14:17], v[156:159], v[246:249], v[14:17]
	s_setprio 0
	s_waitcnt vmcnt(0)
	s_barrier
	s_add_i32 s49, s49, 1
	s_cmp_lt_u32 s49, 16
	s_cbranch_scc1 .Lp8k_B_loop

; #define PG8_STAGE(bufoff, gbase, voff) do { _Pragma("unroll") for (int _i = 0; _i < 2; ++_i) \
;         __builtin_amdgcn_global_load_lds((const unsigned*)((const char*)(gbase) + (voff)[_i]), (PG8_LAS unsigned*)(lds + (bufoff) + ldsw + _i * 8192), 16, 0, 0); } while (0)
; #define PG8_LDA(dst, b, h) do { _Pragma("unroll") for (int m = 0; m < 4; ++m) _Pragma("unroll") for (int k = 0; k < 2; ++k) dst[m][k] = *(const PG8_LAS bf16x8*)(lds + PG8_SA(b, h) + aoff + m * 2048 + k * 1024); } while (0)
; #define PG8_LDB(dst, b, h) do { _Pragma("unroll") for (int n = 0; n < 2; ++n) _Pragma("unroll") for (int k = 0; k < 2; ++k) dst[n][k] = *(const PG8_LAS bf16x8*)(lds + PG8_SB(b, h) + boff + n * 2048 + k * 1024); } while (0)
; #define PG8_WAIT_V(n) asm volatile("s_waitcnt vmcnt(" #n ")" ::: "memory")
; #define PG8_WAIT_L(n) asm volatile("s_waitcnt lgkmcnt(" #n ")" ::: "memory")
; template <class Epi, class Sched, bool ALIGN_EPI>
; __device__ __forceinline__ void gemm_phase(PG8_LAS unsigned char* lds, const Gemm g, const Sched& S, const Epi& E) {
;     ...
;             const char* a1 = cA + (size_t)(t + 1) * kstepA;
;             const char* a2 = last ? nA : cA + (size_t)(t + 2) * kstepA; const char* b2 = last ? nB : cB + (size_t)(t + 2) * kstep;
;             const char* a3 = a2 + kstepA; const char* b3 = b2 + kstep;
;             PG8_LDB(B0, 0, 0); PG8_LDB(B1, 0, 1); PG8_SCHED; PG8_LDA(At, 0, 0); PG8_STAGE(PG8_SA(1, 1), a1 + hstepA, voffA);
;             PG8_WAIT_V(8); PG8_WAIT_L(0); PG8_BAR; PG8_MMA(0, 0, At, B0); PG8_MMA(0, 1, At, B1); PG8_BAR; PG8_SCHED;
;             PG8_LDA(At, 0, 1); PG8_STAGE(PG8_SB(0, 0), b2, voffB); PG8_STAGE(PG8_SB(0, 1), b2 + hstepB, voffB); PG8_STAGE(PG8_SA(0, 0), a2, voffA);
;             PG8_WAIT_V(8); PG8_WAIT_L(0); PG8_BAR; PG8_MMA(1, 0, At, B0); PG8_MMA(1, 1, At, B1); PG8_BAR; PG8_SCHED;
;             PG8_LDB(B0, 1, 0); PG8_LDB(B1, 1, 1); PG8_SCHED; PG8_LDA(At, 1, 0); PG8_STAGE(PG8_SA(0, 1), a2 + hstepA, voffA);
;             PG8_WAIT_V(8); PG8_WAIT_L(0); PG8_BAR; PG8_MMA(0, 0, At, B0); PG8_MMA(0, 1, At, B1); PG8_BAR; PG8_SCHED;
;             PG8_LDA(At, 1, 1); PG8_STAGE(PG8_SB(1, 0), b3, voffB); PG8_STAGE(PG8_SB(1, 1), b3 + hstepB, voffB); PG8_STAGE(PG8_SA(1, 0), a3, voffA);
;             PG8_WAIT_V(8); PG8_WAIT_L(0); PG8_BAR; PG8_MMA(1, 0, At, B0); PG8_MMA(1, 1, At, B1); PG8_BAR; PG8_SCHED;
;         }
.Lp9k_A_loop:
	ds_read_b128 v[194:197], v157 offset:0
	ds_read_b128 v[198:201], v157 offset:1024
	ds_read_b128 v[202:205], v157 offset:2048
	s_add_i32 m0, s60, 0x18000
	s_nop 0
	global_load_lds_dwordx4 v132, s[28:29]
	s_sleep 1
	ds_read_b128 v[206:209], v157 offset:3072
	ds_read_b128 v[210:213], v157 offset:4096
	ds_read_b128 v[214:217], v157 offset:5120
	s_add_i32 m0, s60, 0x1a000
	s_nop 0
	global_load_lds_dwordx4 v136, s[28:29]
	s_sleep 1
	ds_read_b128 v[218:221], v157 offset:6144
	ds_read_b128 v[222:225], v157 offset:7168
	ds_read_b128 v[158:161], v155 offset:0
	s_add_u32 s30, s28, 0x58000
	s_addc_u32 s31, s29, 0
	s_add_i32 m0, s60, 0x19000
	s_nop 0
	global_load_lds_dwordx4 v132, s[30:31]
	s_sleep 1
	ds_read_b128 v[162:165], v155 offset:1024
	ds_read_b128 v[166:169], v155 offset:2048
	ds_read_b128 v[174:177], v155 offset:3072
	s_add_i32 m0, s60, 0x1b000
	s_nop 0
	global_load_lds_dwordx4 v136, s[30:31]
	s_sleep 1
	ds_read_b128 v[178:181], v155 offset:16384
	ds_read_b128 v[182:185], v155 offset:17408
	ds_read_b128 v[186:189], v155 offset:18432
	s_add_u32 s30, s28, 0x160000
	s_addc_u32 s31, s29, 0
	s_add_i32 m0, s60, 0x1c000
	s_nop 0
	global_load_lds_dwordx4 v132, s[30:31]
	s_sleep 1
	ds_read_b128 v[190:193], v155 offset:19456
	ds_read_b128 v[226:229], v157 offset:16384
	ds_read_b128 v[230:233], v157 offset:17408
	s_add_i32 m0, s60, 0x1e000
	s_nop 0
	global_load_lds_dwordx4 v136, s[30:31]
	s_sleep 1
	ds_read_b128 v[234:237], v157 offset:18432
	ds_read_b128 v[238:241], v157 offset:19456
	ds_read_b128 v[242:245], v157 offset:20480
	s_add_u32 s30, s28, 0x1b8000
	s_addc_u32 s31, s29, 0
	s_add_i32 m0, s60, 0x1d000
	s_nop 0
	global_load_lds_dwordx4 v132, s[30:31]
	s_sleep 1
	ds_read_b128 v[246:249], v157 offset:21504
	ds_read_b128 v[250:253], v157 offset:22528
	ds_read_b128 v[142:145], v157 offset:23552
	s_add_i32 m0, s60, 0x1f000
	s_nop 0
	global_load_lds_dwordx4 v136, s[30:31]
	s_add_u32 s28, s28, 0x80
	s_addc_u32 s29, s29, 0
	s_waitcnt vmcnt(8) lgkmcnt(0)
	s_barrier
	s_setprio 1
	v_mfma_f32_16x16x32_bf16 v[126:129], v[158:161], v[194:197], v[126:129]
	v_mfma_f32_16x16x32_bf16 v[126:129], v[162:165], v[198:201], v[126:129]
	v_mfma_f32_16x16x32_bf16 v[122:125], v[174:177], v[198:201], v[122:125]
	v_mfma_f32_16x16x32_bf16 v[122:125], v[166:169], v[194:197], v[122:125]
	v_mfma_f32_16x16x32_bf16 v[114:117], v[178:181], v[194:197], v[114:117]
	v_mfma_f32_16x16x32_bf16 v[114:117], v[182:185], v[198:201], v[114:117]
	v_mfma_f32_16x16x32_bf16 v[106:109], v[190:193], v[198:201], v[106:109]
	v_mfma_f32_16x16x32_bf16 v[106:109], v[186:189], v[194:197], v[106:109]
	v_mfma_f32_16x16x32_bf16 v[90:93], v[186:189], v[202:205], v[90:93]
	v_mfma_f32_16x16x32_bf16 v[90:93], v[190:193], v[206:209], v[90:93]
	v_mfma_f32_16x16x32_bf16 v[98:101], v[182:185], v[206:209], v[98:101]
	v_mfma_f32_16x16x32_bf16 v[98:101], v[178:181], v[202:205], v[98:101]
	v_mfma_f32_16x16x32_bf16 v[110:113], v[166:169], v[202:205], v[110:113]
	v_mfma_f32_16x16x32_bf16 v[110:113], v[174:177], v[206:209], v[110:113]
	v_mfma_f32_16x16x32_bf16 v[118:121], v[162:165], v[206:209], v[118:121]
	v_mfma_f32_16x16x32_bf16 v[118:121], v[158:161], v[202:205], v[118:121]
	v_mfma_f32_16x16x32_bf16 v[102:105], v[158:161], v[210:213], v[102:105]
	v_mfma_f32_16x16x32_bf16 v[102:105], v[162:165], v[214:217], v[102:105]
	v_mfma_f32_16x16x32_bf16 v[94:97], v[174:177], v[214:217], v[94:97]
	v_mfma_f32_16x16x32_bf16 v[94:97], v[166:169], v[210:213], v[94:97]
	v_mfma_f32_16x16x32_bf16 v[82:85], v[178:181], v[210:213], v[82:85]
	v_mfma_f32_16x16x32_bf16 v[82:85], v[182:185], v[214:217], v[82:85]
	v_mfma_f32_16x16x32_bf16 v[74:77], v[190:193], v[214:217], v[74:77]
	v_mfma_f32_16x16x32_bf16 v[74:77], v[186:189], v[210:213], v[74:77]
	v_mfma_f32_16x16x32_bf16 v[66:69], v[186:189], v[218:221], v[66:69]
	v_mfma_f32_16x16x32_bf16 v[66:69], v[190:193], v[222:225], v[66:69]
	v_mfma_f32_16x16x32_bf16 v[70:73], v[182:185], v[222:225], v[70:73]
	v_mfma_f32_16x16x32_bf16 v[70:73], v[178:181], v[218:221], v[70:73]
	v_mfma_f32_16x16x32_bf16 v[78:81], v[166:169], v[218:221], v[78:81]
	v_mfma_f32_16x16x32_bf16 v[78:81], v[174:177], v[222:225], v[78:81]
	v_mfma_f32_16x16x32_bf16 v[86:89], v[162:165], v[222:225], v[86:89]
	v_mfma_f32_16x16x32_bf16 v[86:89], v[158:161], v[218:221], v[86:89]
	v_mfma_f32_16x16x32_bf16 v[62:65], v[158:161], v[226:229], v[62:65]
	v_mfma_f32_16x16x32_bf16 v[62:65], v[162:165], v[230:233], v[62:65]
	v_mfma_f32_16x16x32_bf16 v[58:61], v[174:177], v[230:233], v[58:61]
	v_mfma_f32_16x16x32_bf16 v[58:61], v[166:169], v[226:229], v[58:61]
	v_mfma_f32_16x16x32_bf16 v[50:53], v[178:181], v[226:229], v[50:53]
	v_mfma_f32_16x16x32_bf16 v[50:53], v[182:185], v[230:233], v[50:53]
	v_mfma_f32_16x16x32_bf16 v[42:45], v[190:193], v[230:233], v[42:45]
	v_mfma_f32_16x16x32_bf16 v[42:45], v[186:189], v[226:229], v[42:45]
	v_mfma_f32_16x16x32_bf16 v[26:29], v[186:189], v[234:237], v[26:29]
	v_mfma_f32_16x16x32_bf16 v[26:29], v[190:193], v[238:241], v[26:29]
	v_mfma_f32_16x16x32_bf16 v[34:37], v[182:185], v[238:241], v[34:37]
	v_mfma_f32_16x16x32_bf16 v[34:37], v[178:181], v[234:237], v[34:37]
	v_mfma_f32_16x16x32_bf16 v[46:49], v[166:169], v[234:237], v[46:49]
	v_mfma_f32_16x16x32_bf16 v[46:49], v[174:177], v[238:241], v[46:49]
	v_mfma_f32_16x16x32_bf16 v[54:57], v[162:165], v[238:241], v[54:57]
	v_mfma_f32_16x16x32_bf16 v[54:57], v[158:161], v[234:237], v[54:57]
	v_mfma_f32_16x16x32_bf16 v[38:41], v[158:161], v[242:245], v[38:41]
	v_mfma_f32_16x16x32_bf16 v[38:41], v[162:165], v[246:249], v[38:41]
	v_mfma_f32_16x16x32_bf16 v[30:33], v[174:177], v[246:249], v[30:33]
	v_mfma_f32_16x16x32_bf16 v[30:33], v[166:169], v[242:245], v[30:33]
	v_mfma_f32_16x16x32_bf16 v[18:21], v[178:181], v[242:245], v[18:21]
	v_mfma_f32_16x16x32_bf16 v[18:21], v[182:185], v[246:249], v[18:21]
	v_mfma_f32_16x16x32_bf16 v[10:13], v[190:193], v[246:249], v[10:13]
	v_mfma_f32_16x16x32_bf16 v[10:13], v[186:189], v[242:245], v[10:13]
	v_mfma_f32_16x16x32_bf16 v[2:5], v[186:189], v[250:253], v[2:5]
	v_mfma_f32_16x16x32_bf16 v[2:5], v[190:193], v[142:145], v[2:5]
	v_mfma_f32_16x16x32_bf16 v[6:9], v[182:185], v[142:145], v[6:9]
	v_mfma_f32_16x16x32_bf16 v[6:9], v[178:181], v[250:253], v[6:9]
	v_mfma_f32_16x16x32_bf16 v[14:17], v[166:169], v[250:253], v[14:17]
	v_mfma_f32_16x16x32_bf16 v[14:17], v[174:177], v[142:145], v[14:17]
	v_mfma_f32_16x16x32_bf16 v[22:25], v[162:165], v[142:145], v[22:25]
	v_mfma_f32_16x16x32_bf16 v[22:25], v[158:161], v[250:253], v[22:25]
	s_setprio 0
	s_waitcnt vmcnt(0)
	s_barrier
; #define PG8_STAGE(bufoff, gbase, voff) do { _Pragma("unroll") for (int _i = 0; _i < 2; ++_i) \
;         __builtin_amdgcn_global_load_lds((const unsigned*)((const char*)(gbase) + (voff)[_i]), (PG8_LAS unsigned*)(lds + (bufoff) + ldsw + _i * 8192), 16, 0, 0); } while (0)
; #define PG8_LDA(dst, b, h) do { _Pragma("unroll") for (int m = 0; m < 4; ++m) _Pragma("unroll") for (int k = 0; k < 2; ++k) dst[m][k] = *(const PG8_LAS bf16x8*)(lds + PG8_SA(b, h) + aoff + m * 2048 + k * 1024); } while (0)
; #define PG8_LDB(dst, b, h) do { _Pragma("unroll") for (int n = 0; n < 2; ++n) _Pragma("unroll") for (int k = 0; k < 2; ++k) dst[n][k] = *(const PG8_LAS bf16x8*)(lds + PG8_SB(b, h) + boff + n * 2048 + k * 1024); } while (0)
; #define PG8_WAIT_V(n) asm volatile("s_waitcnt vmcnt(" #n ")" ::: "memory")
; #define PG8_WAIT_L(n) asm volatile("s_waitcnt lgkmcnt(" #n ")" ::: "memory")
; template <class Epi, class Sched, bool ALIGN_EPI>
; __device__ __forceinline__ void gemm_phase(PG8_LAS unsigned char* lds, const Gemm g, const Sched& S, const Epi& E) {
;     ...
;             const char* a1 = cA + (size_t)(t + 1) * kstepA;
;             const char* a2 = last ? nA : cA + (size_t)(t + 2) * kstepA; const char* b2 = last ? nB : cB + (size_t)(t + 2) * kstep;
;             const char* a3 = a2 + kstepA; const char* b3 = b2 + kstep;
;             PG8_LDB(B0, 0, 0); PG8_LDB(B1, 0, 1); PG8_SCHED; PG8_LDA(At, 0, 0); PG8_STAGE(PG8_SA(1, 1), a1 + hstepA, voffA);
;             PG8_WAIT_V(8); PG8_WAIT_L(0); PG8_BAR; PG8_MMA(0, 0, At, B0); PG8_MMA(0, 1, At, B1); PG8_BAR; PG8_SCHED;
;             PG8_LDA(At, 0, 1); PG8_STAGE(PG8_SB(0, 0), b2, voffB); PG8_STAGE(PG8_SB(0, 1), b2 + hstepB, voffB); PG8_STAGE(PG8_SA(0, 0), a2, voffA);
;             PG8_WAIT_V(8); PG8_WAIT_L(0); PG8_BAR; PG8_MMA(1, 0, At, B0); PG8_MMA(1, 1, At, B1); PG8_BAR; PG8_SCHED;
;             PG8_LDB(B0, 1, 0); PG8_LDB(B1, 1, 1); PG8_SCHED; PG8_LDA(At, 1, 0); PG8_STAGE(PG8_SA(0, 1), a2 + hstepA, voffA);
;             PG8_WAIT_V(8); PG8_WAIT_L(0); PG8_BAR; PG8_MMA(0, 0, At, B0); PG8_MMA(0, 1, At, B1); PG8_BAR; PG8_SCHED;
;             PG8_LDA(At, 1, 1); PG8_STAGE(PG8_SB(1, 0), b3, voffB); PG8_STAGE(PG8_SB(1, 1), b3 + hstepB, voffB); PG8_STAGE(PG8_SA(1, 0), a3, voffA);
;             PG8_WAIT_V(8); PG8_WAIT_L(0); PG8_BAR; PG8_MMA(1, 0, At, B0); PG8_MMA(1, 1, At, B1); PG8_BAR; PG8_SCHED;
;         }
	ds_read_b128 v[194:197], v157 offset:32768
	ds_read_b128 v[198:201], v157 offset:33792
	ds_read_b128 v[202:205], v157 offset:34816
	s_cmp_eq_u32 s57, 43
	s_cselect_b32 s28, s58, s28
	s_cselect_b32 s29, s59, s29
	s_add_i32 m0, s60, 0x10000
	s_nop 0
	global_load_lds_dwordx4 v132, s[28:29]
	s_sleep 1
	ds_read_b128 v[206:209], v157 offset:35840
	ds_read_b128 v[210:213], v157 offset:36864
	ds_read_b128 v[214:217], v157 offset:37888
	s_add_i32 m0, s60, 0x12000
	s_nop 0
	global_load_lds_dwordx4 v136, s[28:29]
	s_sleep 1
	ds_read_b128 v[218:221], v157 offset:38912
	ds_read_b128 v[222:225], v157 offset:39936
	ds_read_b128 v[158:161], v155 offset:32768
	s_add_u32 s30, s28, 0x58000
	s_addc_u32 s31, s29, 0
	s_add_i32 m0, s60, 0x11000
	s_nop 0
	global_load_lds_dwordx4 v132, s[30:31]
	s_sleep 1
	ds_read_b128 v[162:165], v155 offset:33792
	ds_read_b128 v[166:169], v155 offset:34816
	ds_read_b128 v[174:177], v155 offset:35840
	s_add_i32 m0, s60, 0x13000
	s_nop 0
	global_load_lds_dwordx4 v136, s[30:31]
	s_sleep 1
	ds_read_b128 v[178:181], v155 offset:49152
	ds_read_b128 v[182:185], v155 offset:50176
	ds_read_b128 v[186:189], v155 offset:51200
	s_add_u32 s30, s28, 0x160000
	s_addc_u32 s31, s29, 0
	s_add_i32 m0, s60, 0x14000
	s_nop 0
	global_load_lds_dwordx4 v132, s[30:31]
	s_sleep 1
	ds_read_b128 v[190:193], v155 offset:52224
	ds_read_b128 v[226:229], v157 offset:49152
	ds_read_b128 v[230:233], v157 offset:50176
	s_add_i32 m0, s60, 0x16000
	s_nop 0
	global_load_lds_dwordx4 v136, s[30:31]
	s_sleep 1
	ds_read_b128 v[234:237], v157 offset:51200
	ds_read_b128 v[238:241], v157 offset:52224
	ds_read_b128 v[242:245], v157 offset:53248
	s_add_u32 s30, s28, 0x1b8000
	s_addc_u32 s31, s29, 0
	s_add_i32 m0, s60, 0x15000
	s_nop 0
	global_load_lds_dwordx4 v132, s[30:31]
	s_sleep 1
	ds_read_b128 v[246:249], v157 offset:54272
	ds_read_b128 v[250:253], v157 offset:55296
	ds_read_b128 v[142:145], v157 offset:56320
	s_add_i32 m0, s60, 0x17000
	s_nop 0
	global_load_lds_dwordx4 v136, s[30:31]
	s_add_u32 s28, s28, 0x80
	s_addc_u32 s29, s29, 0
	s_waitcnt vmcnt(8) lgkmcnt(0)
	s_barrier
	s_setprio 1
	v_mfma_f32_16x16x32_bf16 v[126:129], v[158:161], v[194:197], v[126:129]
	v_mfma_f32_16x16x32_bf16 v[126:129], v[162:165], v[198:201], v[126:129]
	v_mfma_f32_16x16x32_bf16 v[122:125], v[174:177], v[198:201], v[122:125]
	v_mfma_f32_16x16x32_bf16 v[122:125], v[166:169], v[194:197], v[122:125]
	v_mfma_f32_16x16x32_bf16 v[114:117], v[178:181], v[194:197], v[114:117]
	v_mfma_f32_16x16x32_bf16 v[114:117], v[182:185], v[198:201], v[114:117]
	v_mfma_f32_16x16x32_bf16 v[106:109], v[190:193], v[198:201], v[106:109]
	v_mfma_f32_16x16x32_bf16 v[106:109], v[186:189], v[194:197], v[106:109]
	v_mfma_f32_16x16x32_bf16 v[90:93], v[186:189], v[202:205], v[90:93]
	v_mfma_f32_16x16x32_bf16 v[90:93], v[190:193], v[206:209], v[90:93]
	v_mfma_f32_16x16x32_bf16 v[98:101], v[182:185], v[206:209], v[98:101]
	v_mfma_f32_16x16x32_bf16 v[98:101], v[178:181], v[202:205], v[98:101]
	v_mfma_f32_16x16x32_bf16 v[110:113], v[166:169], v[202:205], v[110:113]
	v_mfma_f32_16x16x32_bf16 v[110:113], v[174:177], v[206:209], v[110:113]
	v_mfma_f32_16x16x32_bf16 v[118:121], v[162:165], v[206:209], v[118:121]
	v_mfma_f32_16x16x32_bf16 v[118:121], v[158:161], v[202:205], v[118:121]
	v_mfma_f32_16x16x32_bf16 v[102:105], v[158:161], v[210:213], v[102:105]
	v_mfma_f32_16x16x32_bf16 v[102:105], v[162:165], v[214:217], v[102:105]
	v_mfma_f32_16x16x32_bf16 v[94:97], v[174:177], v[214:217], v[94:97]
	v_mfma_f32_16x16x32_bf16 v[94:97], v[166:169], v[210:213], v[94:97]
	v_mfma_f32_16x16x32_bf16 v[82:85], v[178:181], v[210:213], v[82:85]
	v_mfma_f32_16x16x32_bf16 v[82:85], v[182:185], v[214:217], v[82:85]
	v_mfma_f32_16x16x32_bf16 v[74:77], v[190:193], v[214:217], v[74:77]
	v_mfma_f32_16x16x32_bf16 v[74:77], v[186:189], v[210:213], v[74:77]
	v_mfma_f32_16x16x32_bf16 v[66:69], v[186:189], v[218:221], v[66:69]
	v_mfma_f32_16x16x32_bf16 v[66:69], v[190:193], v[222:225], v[66:69]
	v_mfma_f32_16x16x32_bf16 v[70:73], v[182:185], v[222:225], v[70:73]
	v_mfma_f32_16x16x32_bf16 v[70:73], v[178:181], v[218:221], v[70:73]
	v_mfma_f32_16x16x32_bf16 v[78:81], v[166:169], v[218:221], v[78:81]
	v_mfma_f32_16x16x32_bf16 v[78:81], v[174:177], v[222:225], v[78:81]
	v_mfma_f32_16x16x32_bf16 v[86:89], v[162:165], v[222:225], v[86:89]
	v_mfma_f32_16x16x32_bf16 v[86:89], v[158:161], v[218:221], v[86:89]
	v_mfma_f32_16x16x32_bf16 v[62:65], v[158:161], v[226:229], v[62:65]
	v_mfma_f32_16x16x32_bf16 v[62:65], v[162:165], v[230:233], v[62:65]
	v_mfma_f32_16x16x32_bf16 v[58:61], v[174:177], v[230:233], v[58:61]
	v_mfma_f32_16x16x32_bf16 v[58:61], v[166:169], v[226:229], v[58:61]
	v_mfma_f32_16x16x32_bf16 v[50:53], v[178:181], v[226:229], v[50:53]
	v_mfma_f32_16x16x32_bf16 v[50:53], v[182:185], v[230:233], v[50:53]
	v_mfma_f32_16x16x32_bf16 v[42:45], v[190:193], v[230:233], v[42:45]
	v_mfma_f32_16x16x32_bf16 v[42:45], v[186:189], v[226:229], v[42:45]
	v_mfma_f32_16x16x32_bf16 v[26:29], v[186:189], v[234:237], v[26:29]
	v_mfma_f32_16x16x32_bf16 v[26:29], v[190:193], v[238:241], v[26:29]
	v_mfma_f32_16x16x32_bf16 v[34:37], v[182:185], v[238:241], v[34:37]
	v_mfma_f32_16x16x32_bf16 v[34:37], v[178:181], v[234:237], v[34:37]
	v_mfma_f32_16x16x32_bf16 v[46:49], v[166:169], v[234:237], v[46:49]
	v_mfma_f32_16x16x32_bf16 v[46:49], v[174:177], v[238:241], v[46:49]
	v_mfma_f32_16x16x32_bf16 v[54:57], v[162:165], v[238:241], v[54:57]
	v_mfma_f32_16x16x32_bf16 v[54:57], v[158:161], v[234:237], v[54:57]
	v_mfma_f32_16x16x32_bf16 v[38:41], v[158:161], v[242:245], v[38:41]
	v_mfma_f32_16x16x32_bf16 v[38:41], v[162:165], v[246:249], v[38:41]
	v_mfma_f32_16x16x32_bf16 v[30:33], v[174:177], v[246:249], v[30:33]
	v_mfma_f32_16x16x32_bf16 v[30:33], v[166:169], v[242:245], v[30:33]
	v_mfma_f32_16x16x32_bf16 v[18:21], v[178:181], v[242:245], v[18:21]
	v_mfma_f32_16x16x32_bf16 v[18:21], v[182:185], v[246:249], v[18:21]
	v_mfma_f32_16x16x32_bf16 v[10:13], v[190:193], v[246:249], v[10:13]
	v_mfma_f32_16x16x32_bf16 v[10:13], v[186:189], v[242:245], v[10:13]
	v_mfma_f32_16x16x32_bf16 v[2:5], v[186:189], v[250:253], v[2:5]
	v_mfma_f32_16x16x32_bf16 v[2:5], v[190:193], v[142:145], v[2:5]
	v_mfma_f32_16x16x32_bf16 v[6:9], v[182:185], v[142:145], v[6:9]
	v_mfma_f32_16x16x32_bf16 v[6:9], v[178:181], v[250:253], v[6:9]
	v_mfma_f32_16x16x32_bf16 v[14:17], v[166:169], v[250:253], v[14:17]
	v_mfma_f32_16x16x32_bf16 v[14:17], v[174:177], v[142:145], v[14:17]
	v_mfma_f32_16x16x32_bf16 v[22:25], v[162:165], v[142:145], v[22:25]
	v_mfma_f32_16x16x32_bf16 v[22:25], v[158:161], v[250:253], v[22:25]
	s_setprio 0
	s_waitcnt vmcnt(0)
	s_barrier
	s_add_i32 s57, s57, 1
	s_cmp_lt_u32 s57, 44
	s_cbranch_scc1 .Lp9k_A_loop
	s_branch .Lp9k_done

; #define PG8_STAGE(bufoff, gbase, voff) do { _Pragma("unroll") for (int _i = 0; _i < 2; ++_i) \
;         __builtin_amdgcn_global_load_lds((const unsigned*)((const char*)(gbase) + (voff)[_i]), (PG8_LAS unsigned*)(lds + (bufoff) + ldsw + _i * 8192), 16, 0, 0); } while (0)
; #define PG8_LDA(dst, b, h) do { _Pragma("unroll") for (int m = 0; m < 4; ++m) _Pragma("unroll") for (int k = 0; k < 2; ++k) dst[m][k] = *(const PG8_LAS bf16x8*)(lds + PG8_SA(b, h) + aoff + m * 2048 + k * 1024); } while (0)
; #define PG8_LDB(dst, b, h) do { _Pragma("unroll") for (int n = 0; n < 2; ++n) _Pragma("unroll") for (int k = 0; k < 2; ++k) dst[n][k] = *(const PG8_LAS bf16x8*)(lds + PG8_SB(b, h) + boff + n * 2048 + k * 1024); } while (0)
; #define PG8_WAIT_V(n) asm volatile("s_waitcnt vmcnt(" #n ")" ::: "memory")
; #define PG8_WAIT_L(n) asm volatile("s_waitcnt lgkmcnt(" #n ")" ::: "memory")
; template <class Epi, class Sched, bool ALIGN_EPI>
; __device__ __forceinline__ void gemm_phase(PG8_LAS unsigned char* lds, const Gemm g, const Sched& S, const Epi& E) {
;     ...
;             const char* a1 = cA + (size_t)(t + 1) * kstepA;
;             const char* a2 = last ? nA : cA + (size_t)(t + 2) * kstepA; const char* b2 = last ? nB : cB + (size_t)(t + 2) * kstep;
;             const char* a3 = a2 + kstepA; const char* b3 = b2 + kstep;
;             PG8_LDB(B0, 0, 0); PG8_LDB(B1, 0, 1); PG8_SCHED; PG8_LDA(At, 0, 0); PG8_STAGE(PG8_SA(1, 1), a1 + hstepA, voffA);
;             PG8_WAIT_V(8); PG8_WAIT_L(0); PG8_BAR; PG8_MMA(0, 0, At, B0); PG8_MMA(0, 1, At, B1); PG8_BAR; PG8_SCHED;
;             PG8_LDA(At, 0, 1); PG8_STAGE(PG8_SB(0, 0), b2, voffB); PG8_STAGE(PG8_SB(0, 1), b2 + hstepB, voffB); PG8_STAGE(PG8_SA(0, 0), a2, voffA);
;             PG8_WAIT_V(8); PG8_WAIT_L(0); PG8_BAR; PG8_MMA(1, 0, At, B0); PG8_MMA(1, 1, At, B1); PG8_BAR; PG8_SCHED;
;             PG8_LDB(B0, 1, 0); PG8_LDB(B1, 1, 1); PG8_SCHED; PG8_LDA(At, 1, 0); PG8_STAGE(PG8_SA(0, 1), a2 + hstepA, voffA);
;             PG8_WAIT_V(8); PG8_WAIT_L(0); PG8_BAR; PG8_MMA(0, 0, At, B0); PG8_MMA(0, 1, At, B1); PG8_BAR; PG8_SCHED;
;             PG8_LDA(At, 1, 1); PG8_STAGE(PG8_SB(1, 0), b3, voffB); PG8_STAGE(PG8_SB(1, 1), b3 + hstepB, voffB); PG8_STAGE(PG8_SA(1, 0), a3, voffA);
;             PG8_WAIT_V(8); PG8_WAIT_L(0); PG8_BAR; PG8_MMA(1, 0, At, B0); PG8_MMA(1, 1, At, B1); PG8_BAR; PG8_SCHED;
;         }
.Lp9k_B_loop:
	ds_read_b128 v[194:197], v157 offset:0
	ds_read_b128 v[198:201], v157 offset:1024
	ds_read_b128 v[202:205], v157 offset:2048
	s_add_i32 m0, s60, 0xa000
	s_nop 0
	global_load_lds_dwordx4 v134, s[28:29]
	s_sleep 1
	ds_read_b128 v[206:209], v157 offset:3072
	ds_read_b128 v[210:213], v157 offset:4096
	ds_read_b128 v[214:217], v157 offset:5120
	s_add_u32 s30, s28, 0x58000
	s_addc_u32 s31, s29, 0
	s_add_i32 m0, s60, 0xb000
	s_nop 0
	global_load_lds_dwordx4 v134, s[30:31]
	s_sleep 1
	ds_read_b128 v[218:221], v157 offset:6144
	ds_read_b128 v[222:225], v157 offset:7168
	ds_read_b128 v[158:161], v155 offset:0
	s_add_u32 s30, s28, 0x160000
	s_addc_u32 s31, s29, 0
	s_add_i32 m0, s60, 0xe000
	s_nop 0
	global_load_lds_dwordx4 v134, s[30:31]
	s_sleep 1
	ds_read_b128 v[162:165], v155 offset:1024
	ds_read_b128 v[166:169], v155 offset:2048
	ds_read_b128 v[174:177], v155 offset:3072
	s_add_u32 s30, s28, 0x1b8000
	s_addc_u32 s31, s29, 0
	s_add_i32 m0, s60, 0xf000
	s_nop 0
	global_load_lds_dwordx4 v134, s[30:31]
	s_sleep 1
	ds_read_b128 v[178:181], v155 offset:16384
	ds_read_b128 v[182:185], v155 offset:17408
	ds_read_b128 v[186:189], v155 offset:18432
	s_add_u32 s34, s28, 0x80
	s_addc_u32 s35, s29, 0
	s_cmp_eq_u32 s57, 43
	s_cselect_b32 s34, s58, s34
	s_cselect_b32 s35, s59, s35
	s_add_i32 m0, s60, 0x0
	s_nop 0
	global_load_lds_dwordx4 v130, s[34:35]
	s_sleep 1
	ds_read_b128 v[190:193], v155 offset:19456
	ds_read_b128 v[226:229], v157 offset:16384
	ds_read_b128 v[230:233], v157 offset:17408
	s_add_u32 s30, s34, 0x58000
	s_addc_u32 s31, s35, 0
	s_add_i32 m0, s60, 0x1000
	s_nop 0
	global_load_lds_dwordx4 v130, s[30:31]
	s_sleep 1
	ds_read_b128 v[234:237], v157 offset:18432
	ds_read_b128 v[238:241], v157 offset:19456
	ds_read_b128 v[242:245], v157 offset:20480
	s_add_u32 s30, s34, 0x160000
	s_addc_u32 s31, s35, 0
	s_add_i32 m0, s60, 0x4000
	s_nop 0
	global_load_lds_dwordx4 v130, s[30:31]
	s_sleep 1
	ds_read_b128 v[246:249], v157 offset:21504
	ds_read_b128 v[250:253], v157 offset:22528
	ds_read_b128 v[142:145], v157 offset:23552
	s_add_u32 s30, s34, 0x1b8000
	s_addc_u32 s31, s35, 0
	s_add_i32 m0, s60, 0x5000
	s_nop 0
	global_load_lds_dwordx4 v130, s[30:31]
	s_add_u32 s28, s28, 0x80
	s_addc_u32 s29, s29, 0
	s_waitcnt vmcnt(8) lgkmcnt(0)
	s_barrier
	s_setprio 1
	v_mfma_f32_16x16x32_bf16 v[126:129], v[158:161], v[194:197], v[126:129]
	v_mfma_f32_16x16x32_bf16 v[126:129], v[162:165], v[198:201], v[126:129]
	v_mfma_f32_16x16x32_bf16 v[122:125], v[174:177], v[198:201], v[122:125]
	v_mfma_f32_16x16x32_bf16 v[122:125], v[166:169], v[194:197], v[122:125]
	v_mfma_f32_16x16x32_bf16 v[114:117], v[178:181], v[194:197], v[114:117]
	v_mfma_f32_16x16x32_bf16 v[114:117], v[182:185], v[198:201], v[114:117]
	v_mfma_f32_16x16x32_bf16 v[106:109], v[190:193], v[198:201], v[106:109]
	v_mfma_f32_16x16x32_bf16 v[106:109], v[186:189], v[194:197], v[106:109]
	v_mfma_f32_16x16x32_bf16 v[90:93], v[186:189], v[202:205], v[90:93]
	v_mfma_f32_16x16x32_bf16 v[90:93], v[190:193], v[206:209], v[90:93]
	v_mfma_f32_16x16x32_bf16 v[98:101], v[182:185], v[206:209], v[98:101]
	v_mfma_f32_16x16x32_bf16 v[98:101], v[178:181], v[202:205], v[98:101]
	v_mfma_f32_16x16x32_bf16 v[110:113], v[166:169], v[202:205], v[110:113]
	v_mfma_f32_16x16x32_bf16 v[110:113], v[174:177], v[206:209], v[110:113]
	v_mfma_f32_16x16x32_bf16 v[118:121], v[162:165], v[206:209], v[118:121]
	v_mfma_f32_16x16x32_bf16 v[118:121], v[158:161], v[202:205], v[118:121]
	v_mfma_f32_16x16x32_bf16 v[102:105], v[158:161], v[210:213], v[102:105]
	v_mfma_f32_16x16x32_bf16 v[102:105], v[162:165], v[214:217], v[102:105]
	v_mfma_f32_16x16x32_bf16 v[94:97], v[174:177], v[214:217], v[94:97]
	v_mfma_f32_16x16x32_bf16 v[94:97], v[166:169], v[210:213], v[94:97]
	v_mfma_f32_16x16x32_bf16 v[82:85], v[178:181], v[210:213], v[82:85]
	v_mfma_f32_16x16x32_bf16 v[82:85], v[182:185], v[214:217], v[82:85]
	v_mfma_f32_16x16x32_bf16 v[74:77], v[190:193], v[214:217], v[74:77]
	v_mfma_f32_16x16x32_bf16 v[74:77], v[186:189], v[210:213], v[74:77]
	v_mfma_f32_16x16x32_bf16 v[66:69], v[186:189], v[218:221], v[66:69]
	v_mfma_f32_16x16x32_bf16 v[66:69], v[190:193], v[222:225], v[66:69]
	v_mfma_f32_16x16x32_bf16 v[70:73], v[182:185], v[222:225], v[70:73]
	v_mfma_f32_16x16x32_bf16 v[70:73], v[178:181], v[218:221], v[70:73]
	v_mfma_f32_16x16x32_bf16 v[78:81], v[166:169], v[218:221], v[78:81]
	v_mfma_f32_16x16x32_bf16 v[78:81], v[174:177], v[222:225], v[78:81]
	v_mfma_f32_16x16x32_bf16 v[86:89], v[162:165], v[222:225], v[86:89]
	v_mfma_f32_16x16x32_bf16 v[86:89], v[158:161], v[218:221], v[86:89]
	v_mfma_f32_16x16x32_bf16 v[62:65], v[158:161], v[226:229], v[62:65]
	v_mfma_f32_16x16x32_bf16 v[62:65], v[162:165], v[230:233], v[62:65]
	v_mfma_f32_16x16x32_bf16 v[58:61], v[174:177], v[230:233], v[58:61]
	v_mfma_f32_16x16x32_bf16 v[58:61], v[166:169], v[226:229], v[58:61]
	v_mfma_f32_16x16x32_bf16 v[50:53], v[178:181], v[226:229], v[50:53]
	v_mfma_f32_16x16x32_bf16 v[50:53], v[182:185], v[230:233], v[50:53]
	v_mfma_f32_16x16x32_bf16 v[42:45], v[190:193], v[230:233], v[42:45]
	v_mfma_f32_16x16x32_bf16 v[42:45], v[186:189], v[226:229], v[42:45]
	v_mfma_f32_16x16x32_bf16 v[26:29], v[186:189], v[234:237], v[26:29]
	v_mfma_f32_16x16x32_bf16 v[26:29], v[190:193], v[238:241], v[26:29]
	v_mfma_f32_16x16x32_bf16 v[34:37], v[182:185], v[238:241], v[34:37]
	v_mfma_f32_16x16x32_bf16 v[34:37], v[178:181], v[234:237], v[34:37]
	v_mfma_f32_16x16x32_bf16 v[46:49], v[166:169], v[234:237], v[46:49]
	v_mfma_f32_16x16x32_bf16 v[46:49], v[174:177], v[238:241], v[46:49]
	v_mfma_f32_16x16x32_bf16 v[54:57], v[162:165], v[238:241], v[54:57]
	v_mfma_f32_16x16x32_bf16 v[54:57], v[158:161], v[234:237], v[54:57]
	v_mfma_f32_16x16x32_bf16 v[38:41], v[158:161], v[242:245], v[38:41]
	v_mfma_f32_16x16x32_bf16 v[38:41], v[162:165], v[246:249], v[38:41]
	v_mfma_f32_16x16x32_bf16 v[30:33], v[174:177], v[246:249], v[30:33]
	v_mfma_f32_16x16x32_bf16 v[30:33], v[166:169], v[242:245], v[30:33]
	v_mfma_f32_16x16x32_bf16 v[18:21], v[178:181], v[242:245], v[18:21]
	v_mfma_f32_16x16x32_bf16 v[18:21], v[182:185], v[246:249], v[18:21]
	v_mfma_f32_16x16x32_bf16 v[10:13], v[190:193], v[246:249], v[10:13]
	v_mfma_f32_16x16x32_bf16 v[10:13], v[186:189], v[242:245], v[10:13]
	v_mfma_f32_16x16x32_bf16 v[2:5], v[186:189], v[250:253], v[2:5]
	v_mfma_f32_16x16x32_bf16 v[2:5], v[190:193], v[142:145], v[2:5]
	v_mfma_f32_16x16x32_bf16 v[6:9], v[182:185], v[142:145], v[6:9]
	v_mfma_f32_16x16x32_bf16 v[6:9], v[178:181], v[250:253], v[6:9]
	v_mfma_f32_16x16x32_bf16 v[14:17], v[166:169], v[250:253], v[14:17]
	v_mfma_f32_16x16x32_bf16 v[14:17], v[174:177], v[142:145], v[14:17]
	v_mfma_f32_16x16x32_bf16 v[22:25], v[162:165], v[142:145], v[22:25]
	v_mfma_f32_16x16x32_bf16 v[22:25], v[158:161], v[250:253], v[22:25]
	s_setprio 0
	s_waitcnt vmcnt(0)
	s_barrier
; #define PG8_STAGE(bufoff, gbase, voff) do { _Pragma("unroll") for (int _i = 0; _i < 2; ++_i) \
;         __builtin_amdgcn_global_load_lds((const unsigned*)((const char*)(gbase) + (voff)[_i]), (PG8_LAS unsigned*)(lds + (bufoff) + ldsw + _i * 8192), 16, 0, 0); } while (0)
; #define PG8_LDA(dst, b, h) do { _Pragma("unroll") for (int m = 0; m < 4; ++m) _Pragma("unroll") for (int k = 0; k < 2; ++k) dst[m][k] = *(const PG8_LAS bf16x8*)(lds + PG8_SA(b, h) + aoff + m * 2048 + k * 1024); } while (0)
; #define PG8_LDB(dst, b, h) do { _Pragma("unroll") for (int n = 0; n < 2; ++n) _Pragma("unroll") for (int k = 0; k < 2; ++k) dst[n][k] = *(const PG8_LAS bf16x8*)(lds + PG8_SB(b, h) + boff + n * 2048 + k * 1024); } while (0)
; #define PG8_WAIT_V(n) asm volatile("s_waitcnt vmcnt(" #n ")" ::: "memory")
; #define PG8_WAIT_L(n) asm volatile("s_waitcnt lgkmcnt(" #n ")" ::: "memory")
; template <class Epi, class Sched, bool ALIGN_EPI>
; __device__ __forceinline__ void gemm_phase(PG8_LAS unsigned char* lds, const Gemm g, const Sched& S, const Epi& E) {
;     ...
;             const char* a1 = cA + (size_t)(t + 1) * kstepA;
;             const char* a2 = last ? nA : cA + (size_t)(t + 2) * kstepA; const char* b2 = last ? nB : cB + (size_t)(t + 2) * kstep;
;             const char* a3 = a2 + kstepA; const char* b3 = b2 + kstep;
;             PG8_LDB(B0, 0, 0); PG8_LDB(B1, 0, 1); PG8_SCHED; PG8_LDA(At, 0, 0); PG8_STAGE(PG8_SA(1, 1), a1 + hstepA, voffA);
;             PG8_WAIT_V(8); PG8_WAIT_L(0); PG8_BAR; PG8_MMA(0, 0, At, B0); PG8_MMA(0, 1, At, B1); PG8_BAR; PG8_SCHED;
;             PG8_LDA(At, 0, 1); PG8_STAGE(PG8_SB(0, 0), b2, voffB); PG8_STAGE(PG8_SB(0, 1), b2 + hstepB, voffB); PG8_STAGE(PG8_SA(0, 0), a2, voffA);
;             PG8_WAIT_V(8); PG8_WAIT_L(0); PG8_BAR; PG8_MMA(1, 0, At, B0); PG8_MMA(1, 1, At, B1); PG8_BAR; PG8_SCHED;
;             PG8_LDB(B0, 1, 0); PG8_LDB(B1, 1, 1); PG8_SCHED; PG8_LDA(At, 1, 0); PG8_STAGE(PG8_SA(0, 1), a2 + hstepA, voffA);
;             PG8_WAIT_V(8); PG8_WAIT_L(0); PG8_BAR; PG8_MMA(0, 0, At, B0); PG8_MMA(0, 1, At, B1); PG8_BAR; PG8_SCHED;
;             PG8_LDA(At, 1, 1); PG8_STAGE(PG8_SB(1, 0), b3, voffB); PG8_STAGE(PG8_SB(1, 1), b3 + hstepB, voffB); PG8_STAGE(PG8_SA(1, 0), a3, voffA);
;             PG8_WAIT_V(8); PG8_WAIT_L(0); PG8_BAR; PG8_MMA(1, 0, At, B0); PG8_MMA(1, 1, At, B1); PG8_BAR; PG8_SCHED;
;         }
	ds_read_b128 v[194:197], v157 offset:32768
	ds_read_b128 v[198:201], v157 offset:33792
	ds_read_b128 v[202:205], v157 offset:34816
	s_cmp_eq_u32 s57, 43
	s_cselect_b32 s28, s58, s28
	s_cselect_b32 s29, s59, s29
	s_add_i32 m0, s60, 0x2000
	s_nop 0
	global_load_lds_dwordx4 v134, s[28:29]
	s_sleep 1
	ds_read_b128 v[206:209], v157 offset:35840
	ds_read_b128 v[210:213], v157 offset:36864
	ds_read_b128 v[214:217], v157 offset:37888
	s_add_u32 s30, s28, 0x58000
	s_addc_u32 s31, s29, 0
	s_add_i32 m0, s60, 0x3000
	s_nop 0
	global_load_lds_dwordx4 v134, s[30:31]
	s_sleep 1
	ds_read_b128 v[218:221], v157 offset:38912
	ds_read_b128 v[222:225], v157 offset:39936
	ds_read_b128 v[158:161], v155 offset:32768
	s_add_u32 s30, s28, 0x160000
	s_addc_u32 s31, s29, 0
	s_add_i32 m0, s60, 0x6000
	s_nop 0
	global_load_lds_dwordx4 v134, s[30:31]
	s_sleep 1
	ds_read_b128 v[162:165], v155 offset:33792
	ds_read_b128 v[166:169], v155 offset:34816
	ds_read_b128 v[174:177], v155 offset:35840
	s_add_u32 s30, s28, 0x1b8000
	s_addc_u32 s31, s29, 0
	s_add_i32 m0, s60, 0x7000
	s_nop 0
	global_load_lds_dwordx4 v134, s[30:31]
	s_sleep 1
	ds_read_b128 v[178:181], v155 offset:49152
	ds_read_b128 v[182:185], v155 offset:50176
	ds_read_b128 v[186:189], v155 offset:51200
	s_add_u32 s34, s28, 0x80
	s_addc_u32 s35, s29, 0
	s_add_i32 m0, s60, 0x8000
	s_nop 0
	global_load_lds_dwordx4 v130, s[34:35]
	s_sleep 1
	ds_read_b128 v[190:193], v155 offset:52224
	ds_read_b128 v[226:229], v157 offset:49152
	ds_read_b128 v[230:233], v157 offset:50176
	s_add_u32 s30, s34, 0x58000
	s_addc_u32 s31, s35, 0
	s_add_i32 m0, s60, 0x9000
	s_nop 0
	global_load_lds_dwordx4 v130, s[30:31]
	s_sleep 1
	ds_read_b128 v[234:237], v157 offset:51200
	ds_read_b128 v[238:241], v157 offset:52224
	ds_read_b128 v[242:245], v157 offset:53248
	s_add_u32 s30, s34, 0x160000
	s_addc_u32 s31, s35, 0
	s_add_i32 m0, s60, 0xc000
	s_nop 0
	global_load_lds_dwordx4 v130, s[30:31]
	s_sleep 1
	ds_read_b128 v[246:249], v157 offset:54272
	ds_read_b128 v[250:253], v157 offset:55296
	ds_read_b128 v[142:145], v157 offset:56320
	s_add_u32 s30, s34, 0x1b8000
	s_addc_u32 s31, s35, 0
	s_add_i32 m0, s60, 0xd000
	s_nop 0
	global_load_lds_dwordx4 v130, s[30:31]
	s_add_u32 s28, s28, 0x80
	s_addc_u32 s29, s29, 0
	s_waitcnt vmcnt(8) lgkmcnt(0)
	s_barrier
	s_setprio 1
	v_mfma_f32_16x16x32_bf16 v[126:129], v[158:161], v[194:197], v[126:129]
	v_mfma_f32_16x16x32_bf16 v[126:129], v[162:165], v[198:201], v[126:129]
	v_mfma_f32_16x16x32_bf16 v[122:125], v[174:177], v[198:201], v[122:125]
	v_mfma_f32_16x16x32_bf16 v[122:125], v[166:169], v[194:197], v[122:125]
	v_mfma_f32_16x16x32_bf16 v[114:117], v[178:181], v[194:197], v[114:117]
	v_mfma_f32_16x16x32_bf16 v[114:117], v[182:185], v[198:201], v[114:117]
	v_mfma_f32_16x16x32_bf16 v[106:109], v[190:193], v[198:201], v[106:109]
	v_mfma_f32_16x16x32_bf16 v[106:109], v[186:189], v[194:197], v[106:109]
	v_mfma_f32_16x16x32_bf16 v[90:93], v[186:189], v[202:205], v[90:93]
	v_mfma_f32_16x16x32_bf16 v[90:93], v[190:193], v[206:209], v[90:93]
	v_mfma_f32_16x16x32_bf16 v[98:101], v[182:185], v[206:209], v[98:101]
	v_mfma_f32_16x16x32_bf16 v[98:101], v[178:181], v[202:205], v[98:101]
	v_mfma_f32_16x16x32_bf16 v[110:113], v[166:169], v[202:205], v[110:113]
	v_mfma_f32_16x16x32_bf16 v[110:113], v[174:177], v[206:209], v[110:113]
	v_mfma_f32_16x16x32_bf16 v[118:121], v[162:165], v[206:209], v[118:121]
	v_mfma_f32_16x16x32_bf16 v[118:121], v[158:161], v[202:205], v[118:121]
	v_mfma_f32_16x16x32_bf16 v[102:105], v[158:161], v[210:213], v[102:105]
	v_mfma_f32_16x16x32_bf16 v[102:105], v[162:165], v[214:217], v[102:105]
	v_mfma_f32_16x16x32_bf16 v[94:97], v[174:177], v[214:217], v[94:97]
	v_mfma_f32_16x16x32_bf16 v[94:97], v[166:169], v[210:213], v[94:97]
	v_mfma_f32_16x16x32_bf16 v[82:85], v[178:181], v[210:213], v[82:85]
	v_mfma_f32_16x16x32_bf16 v[82:85], v[182:185], v[214:217], v[82:85]
	v_mfma_f32_16x16x32_bf16 v[74:77], v[190:193], v[214:217], v[74:77]
	v_mfma_f32_16x16x32_bf16 v[74:77], v[186:189], v[210:213], v[74:77]
	v_mfma_f32_16x16x32_bf16 v[66:69], v[186:189], v[218:221], v[66:69]
	v_mfma_f32_16x16x32_bf16 v[66:69], v[190:193], v[222:225], v[66:69]
	v_mfma_f32_16x16x32_bf16 v[70:73], v[182:185], v[222:225], v[70:73]
	v_mfma_f32_16x16x32_bf16 v[70:73], v[178:181], v[218:221], v[70:73]
	v_mfma_f32_16x16x32_bf16 v[78:81], v[166:169], v[218:221], v[78:81]
	v_mfma_f32_16x16x32_bf16 v[78:81], v[174:177], v[222:225], v[78:81]
	v_mfma_f32_16x16x32_bf16 v[86:89], v[162:165], v[222:225], v[86:89]
	v_mfma_f32_16x16x32_bf16 v[86:89], v[158:161], v[218:221], v[86:89]
	v_mfma_f32_16x16x32_bf16 v[62:65], v[158:161], v[226:229], v[62:65]
	v_mfma_f32_16x16x32_bf16 v[62:65], v[162:165], v[230:233], v[62:65]
	v_mfma_f32_16x16x32_bf16 v[58:61], v[174:177], v[230:233], v[58:61]
	v_mfma_f32_16x16x32_bf16 v[58:61], v[166:169], v[226:229], v[58:61]
	v_mfma_f32_16x16x32_bf16 v[50:53], v[178:181], v[226:229], v[50:53]
	v_mfma_f32_16x16x32_bf16 v[50:53], v[182:185], v[230:233], v[50:53]
	v_mfma_f32_16x16x32_bf16 v[42:45], v[190:193], v[230:233], v[42:45]
	v_mfma_f32_16x16x32_bf16 v[42:45], v[186:189], v[226:229], v[42:45]
	v_mfma_f32_16x16x32_bf16 v[26:29], v[186:189], v[234:237], v[26:29]
	v_mfma_f32_16x16x32_bf16 v[26:29], v[190:193], v[238:241], v[26:29]
	v_mfma_f32_16x16x32_bf16 v[34:37], v[182:185], v[238:241], v[34:37]
	v_mfma_f32_16x16x32_bf16 v[34:37], v[178:181], v[234:237], v[34:37]
	v_mfma_f32_16x16x32_bf16 v[46:49], v[166:169], v[234:237], v[46:49]
	v_mfma_f32_16x16x32_bf16 v[46:49], v[174:177], v[238:241], v[46:49]
	v_mfma_f32_16x16x32_bf16 v[54:57], v[162:165], v[238:241], v[54:57]
	v_mfma_f32_16x16x32_bf16 v[54:57], v[158:161], v[234:237], v[54:57]
	v_mfma_f32_16x16x32_bf16 v[38:41], v[158:161], v[242:245], v[38:41]
	v_mfma_f32_16x16x32_bf16 v[38:41], v[162:165], v[246:249], v[38:41]
	v_mfma_f32_16x16x32_bf16 v[30:33], v[174:177], v[246:249], v[30:33]
	v_mfma_f32_16x16x32_bf16 v[30:33], v[166:169], v[242:245], v[30:33]
	v_mfma_f32_16x16x32_bf16 v[18:21], v[178:181], v[242:245], v[18:21]
	v_mfma_f32_16x16x32_bf16 v[18:21], v[182:185], v[246:249], v[18:21]
	v_mfma_f32_16x16x32_bf16 v[10:13], v[190:193], v[246:249], v[10:13]
	v_mfma_f32_16x16x32_bf16 v[10:13], v[186:189], v[242:245], v[10:13]
	v_mfma_f32_16x16x32_bf16 v[2:5], v[186:189], v[250:253], v[2:5]
	v_mfma_f32_16x16x32_bf16 v[2:5], v[190:193], v[142:145], v[2:5]
	v_mfma_f32_16x16x32_bf16 v[6:9], v[182:185], v[142:145], v[6:9]
	v_mfma_f32_16x16x32_bf16 v[6:9], v[178:181], v[250:253], v[6:9]
	v_mfma_f32_16x16x32_bf16 v[14:17], v[166:169], v[250:253], v[14:17]
	v_mfma_f32_16x16x32_bf16 v[14:17], v[174:177], v[142:145], v[14:17]
	v_mfma_f32_16x16x32_bf16 v[22:25], v[162:165], v[142:145], v[22:25]
	v_mfma_f32_16x16x32_bf16 v[22:25], v[158:161], v[250:253], v[22:25]
	s_setprio 0
	s_waitcnt vmcnt(0)
	s_barrier
	s_add_i32 s57, s57, 1
	s_cmp_lt_u32 s57, 44
	s_cbranch_scc1 .Lp9k_B_loop
